# MFMA order within each 8-group changed so only one operand changes between neighbours (Gray order), on top of v15
# speedup vs baseline: 1.0011x; 1.0011x over previous
.LBB0_105:
	v_lshlrev_b32_e32 v66, 2, v0
	s_add_u32 s4, s74, 0x400000
	v_lshrrev_b32_e32 v1, 5, v0
	v_and_b32_e32 v66, 0x7c, v66
	s_addc_u32 s5, s75, 0
	s_lshl_b32 s2, s79, 2
	v_mul_u32_u24_e32 v1, 0x210, v1
	v_lshlrev_b32_e32 v67, 2, v66
	s_add_i32 s2, s2, 0
	s_movk_i32 s0, 0x210
	v_add3_u32 v1, 0, v1, v67
	v_lshrrev_b32_e32 v67, 4, v0
	v_mov_b32_e32 v68, s2
	s_mov_b32 s1, 0
	v_and_b32_e32 v67, 30, v67
	v_mad_u32_u24 v102, v222, s0, v68
	s_add_i32 s0, s78, s33
	v_mov_b32_e32 v69, 0
	v_or_b32_e32 v103, 0x80, v67
	s_lshl_b32 s13, s0, 7
	s_lshl_b32 s15, s33, 7
	s_mov_b64 s[6:7], 0
	s_movk_i32 s23, 0xe000
	s_mov_b32 s26, s78
	s_mov_b32 s8, s1
	s_mov_b32 s27, 0
	s_mov_b32 s30, 0
	s_mov_b32 s0, s1
	s_mov_b32 s31, s1
	s_mov_b64 s[10:11], 0
	s_mov_b32 s98, 0
	s_branch .LBB0_107
.Lcva_steady:
	s_waitcnt vmcnt(46)
	v_cvt_pk_bf16_f32 v70, v2, v6
	v_cvt_pk_bf16_f32 v71, v3, v7
	v_cvt_pk_bf16_f32 v72, v4, v8
	v_cvt_pk_bf16_f32 v73, v5, v9
	ds_write_b128 v1, v[70:73]
	s_waitcnt vmcnt(44)
	v_cvt_pk_bf16_f32 v70, v10, v14
	v_cvt_pk_bf16_f32 v71, v11, v15
	v_cvt_pk_bf16_f32 v72, v12, v16
	v_cvt_pk_bf16_f32 v73, v13, v17
	v_cndmask_b32_e64 v68, 0, 1, s[24:25]
	ds_write_b128 v1, v[70:73] offset:8448
	s_waitcnt vmcnt(42)
	v_cvt_pk_bf16_f32 v70, v26, v38
	v_cvt_pk_bf16_f32 v71, v27, v39
	v_cvt_pk_bf16_f32 v72, v28, v40
	v_cvt_pk_bf16_f32 v73, v29, v41
	v_cmp_ne_u32_e64 s[2:3], 1, v68
	s_andn2_b64 vcc, exec, s[24:25]
	ds_write_b128 v1, v[70:73] offset:16896
	s_waitcnt vmcnt(40)
	v_cvt_pk_bf16_f32 v70, v50, v54
	v_cvt_pk_bf16_f32 v71, v51, v55
	v_cvt_pk_bf16_f32 v72, v52, v56
	v_cvt_pk_bf16_f32 v73, v53, v57
	ds_write_b128 v1, v[70:73] offset:25344
	s_cbranch_vccnz .Lcva_snomore
	v_or_b32_e32 v2, s27, v67
	s_ashr_i32 s9, s27, 31
	s_mul_i32 s9, s9, s0
	v_mad_u64_u32 v[2:3], s[24:25], v2, s0, 0
	v_add_u32_e32 v3, s9, v3
	v_lshl_add_u64 v[2:3], v[2:3], 2, s[10:11]
	s_ashr_i32 s9, s8, 31
	v_lshl_add_u64 v[2:3], s[8:9], 2, v[2:3]
	v_lshlrev_b32_e32 v68, 2, v66
	v_lshl_add_u64 v[50:51], v[2:3], 0, v[68:69]
	s_lshl_b32 s24, s0, 5
	s_mov_b32 s25, s1
	v_lshl_add_u64 v[10:11], s[24:25], 2, v[50:51]
	s_mul_i32 s24, s0, 33
	v_lshl_add_u64 v[14:15], s[24:25], 2, v[50:51]
	s_lshl_b32 s24, s0, 6
	v_lshl_add_u64 v[26:27], s[24:25], 2, v[50:51]
	s_mul_i32 s24, s0, 0x41
	v_lshl_add_u64 v[38:39], s[24:25], 2, v[50:51]
	s_mul_i32 s24, s0, 0x60
	v_lshl_add_u64 v[52:53], s[24:25], 2, v[50:51]
	s_mul_i32 s24, s0, 0x61
	v_lshl_add_u64 v[6:7], s[0:1], 2, v[50:51]
	v_lshl_add_u64 v[54:55], s[24:25], 2, v[50:51]
	global_load_dwordx4 v[2:5], v[50:51], off nt
	s_nop 0
	global_load_dwordx4 v[6:9], v[6:7], off nt
	s_nop 0
	global_load_dwordx4 v[10:13], v[10:11], off nt
	s_nop 0
	global_load_dwordx4 v[14:17], v[14:15], off nt
	s_nop 0
	global_load_dwordx4 v[26:29], v[26:27], off nt
	s_nop 0
	global_load_dwordx4 v[38:41], v[38:39], off nt
	s_nop 0
	global_load_dwordx4 v[50:53], v[52:53], off nt
	s_nop 0
	global_load_dwordx4 v[54:57], v[54:55], off nt
.Lcva_smid:
	s_waitcnt vmcnt(46)
	v_cvt_pk_bf16_f32 v70, v18, v22
	v_cvt_pk_bf16_f32 v71, v19, v23
	v_cvt_pk_bf16_f32 v72, v20, v24
	v_cvt_pk_bf16_f32 v73, v21, v25
	ds_write_b128 v1, v[70:73] offset:33792
	s_waitcnt vmcnt(44)
	v_cvt_pk_bf16_f32 v70, v30, v34
	v_cvt_pk_bf16_f32 v71, v31, v35
	v_cvt_pk_bf16_f32 v72, v32, v36
	v_cvt_pk_bf16_f32 v73, v33, v37
	ds_write_b128 v1, v[70:73] offset:42240
	s_waitcnt vmcnt(42)
	v_cvt_pk_bf16_f32 v70, v42, v46
	v_cvt_pk_bf16_f32 v71, v43, v47
	v_cvt_pk_bf16_f32 v72, v44, v48
	v_cvt_pk_bf16_f32 v73, v45, v49
	s_and_b64 vcc, exec, s[2:3]
	ds_write_b128 v1, v[70:73] offset:50688
	s_waitcnt vmcnt(40)
	v_cvt_pk_bf16_f32 v70, v58, v62
	v_cvt_pk_bf16_f32 v71, v59, v63
	v_cvt_pk_bf16_f32 v72, v60, v64
	v_cvt_pk_bf16_f32 v73, v61, v65
	ds_write_b128 v1, v[70:73] offset:59136
	s_cbranch_vccnz .LBB0_113
	v_or_b32_e32 v18, s27, v103
	s_ashr_i32 s2, s27, 31
	s_mul_i32 s9, s2, s0
	v_mad_u64_u32 v[18:19], s[2:3], v18, s0, 0
	v_add_u32_e32 v19, s9, v19
	v_lshl_add_u64 v[18:19], v[18:19], 2, s[10:11]
	s_ashr_i32 s9, s8, 31
	v_lshl_add_u64 v[18:19], s[8:9], 2, v[18:19]
	v_lshlrev_b32_e32 v68, 2, v66
	v_lshl_add_u64 v[58:59], v[18:19], 0, v[68:69]
	s_lshl_b32 s2, s0, 5
	s_mov_b32 s3, s1
	v_lshl_add_u64 v[30:31], s[2:3], 2, v[58:59]
	s_mul_i32 s2, s0, 33
	v_lshl_add_u64 v[34:35], s[2:3], 2, v[58:59]
	s_lshl_b32 s2, s0, 6
	v_lshl_add_u64 v[42:43], s[2:3], 2, v[58:59]
	s_mul_i32 s2, s0, 0x41
	v_lshl_add_u64 v[46:47], s[2:3], 2, v[58:59]
	s_mul_i32 s2, s0, 0x60
	v_lshl_add_u64 v[60:61], s[2:3], 2, v[58:59]
	s_mul_i32 s2, s0, 0x61
	v_lshl_add_u64 v[22:23], s[0:1], 2, v[58:59]
	v_lshl_add_u64 v[62:63], s[2:3], 2, v[58:59]
	global_load_dwordx4 v[18:21], v[58:59], off nt
	s_nop 0
	global_load_dwordx4 v[22:25], v[22:23], off nt
	s_nop 0
	global_load_dwordx4 v[30:33], v[30:31], off nt
	s_nop 0
	global_load_dwordx4 v[34:37], v[34:35], off nt
	s_nop 0
	global_load_dwordx4 v[42:45], v[42:43], off nt
	s_nop 0
	global_load_dwordx4 v[46:49], v[46:47], off nt
	s_nop 0
	global_load_dwordx4 v[58:61], v[60:61], off nt
	s_nop 0
	global_load_dwordx4 v[62:65], v[62:63], off nt
	s_branch .LBB0_113
.Lcva_snomore:
	s_waitcnt vmcnt(32)
	s_branch .Lcva_smid
.Lcva_fnomore:
	s_waitcnt vmcnt(0)
	s_branch .LBB0_111

.LBB0_109:
	s_cmp_lg_u32 s98, 0
	s_cbranch_scc1 .Lcva_steady
	s_waitcnt vmcnt(14)
	v_cvt_pk_bf16_f32 v70, v2, v6
	v_cvt_pk_bf16_f32 v71, v3, v7
	v_cvt_pk_bf16_f32 v72, v4, v8
	v_cvt_pk_bf16_f32 v73, v5, v9
	ds_write_b128 v1, v[70:73]
	s_waitcnt vmcnt(12)
	v_cvt_pk_bf16_f32 v70, v10, v14
	v_cvt_pk_bf16_f32 v71, v11, v15
	v_cvt_pk_bf16_f32 v72, v12, v16
	v_cvt_pk_bf16_f32 v73, v13, v17
	v_cndmask_b32_e64 v68, 0, 1, s[24:25]
	ds_write_b128 v1, v[70:73] offset:8448
	s_waitcnt vmcnt(10)
	v_cvt_pk_bf16_f32 v70, v26, v38
	v_cvt_pk_bf16_f32 v71, v27, v39
	v_cvt_pk_bf16_f32 v72, v28, v40
	v_cvt_pk_bf16_f32 v73, v29, v41
	v_cmp_ne_u32_e64 s[2:3], 1, v68
	s_andn2_b64 vcc, exec, s[24:25]
	ds_write_b128 v1, v[70:73] offset:16896
	s_waitcnt vmcnt(8)
	v_cvt_pk_bf16_f32 v70, v50, v54
	v_cvt_pk_bf16_f32 v71, v51, v55
	v_cvt_pk_bf16_f32 v72, v52, v56
	v_cvt_pk_bf16_f32 v73, v53, v57
	ds_write_b128 v1, v[70:73] offset:25344
	s_cbranch_vccnz .Lcva_fnomore
	v_or_b32_e32 v2, s27, v67
	s_ashr_i32 s9, s27, 31
	s_mul_i32 s9, s9, s0
	v_mad_u64_u32 v[2:3], s[24:25], v2, s0, 0
	v_add_u32_e32 v3, s9, v3
	v_lshl_add_u64 v[2:3], v[2:3], 2, s[10:11]
	s_ashr_i32 s9, s8, 31
	v_lshl_add_u64 v[2:3], s[8:9], 2, v[2:3]
	v_lshlrev_b32_e32 v68, 2, v66
	v_lshl_add_u64 v[50:51], v[2:3], 0, v[68:69]
	s_lshl_b32 s24, s0, 5
	s_mov_b32 s25, s1
	v_lshl_add_u64 v[10:11], s[24:25], 2, v[50:51]
	s_mul_i32 s24, s0, 33
	v_lshl_add_u64 v[14:15], s[24:25], 2, v[50:51]
	s_lshl_b32 s24, s0, 6
	v_lshl_add_u64 v[26:27], s[24:25], 2, v[50:51]
	s_mul_i32 s24, s0, 0x41
	v_lshl_add_u64 v[38:39], s[24:25], 2, v[50:51]
	s_mul_i32 s24, s0, 0x60
	v_lshl_add_u64 v[52:53], s[24:25], 2, v[50:51]
	s_mul_i32 s24, s0, 0x61
	v_lshl_add_u64 v[6:7], s[0:1], 2, v[50:51]
	v_lshl_add_u64 v[54:55], s[24:25], 2, v[50:51]
	global_load_dwordx4 v[2:5], v[50:51], off nt
	s_nop 0
	global_load_dwordx4 v[6:9], v[6:7], off nt
	s_nop 0
	global_load_dwordx4 v[10:13], v[10:11], off nt
	s_nop 0
	global_load_dwordx4 v[14:17], v[14:15], off nt
	s_nop 0
	global_load_dwordx4 v[26:29], v[26:27], off nt
	s_nop 0
	global_load_dwordx4 v[38:41], v[38:39], off nt
	s_nop 0
	global_load_dwordx4 v[50:53], v[52:53], off nt
	s_nop 0
	global_load_dwordx4 v[54:57], v[54:55], off nt
.LBB0_111:
	s_waitcnt vmcnt(14)
	v_cvt_pk_bf16_f32 v70, v18, v22
	v_cvt_pk_bf16_f32 v71, v19, v23
	v_cvt_pk_bf16_f32 v72, v20, v24
	v_cvt_pk_bf16_f32 v73, v21, v25
	ds_write_b128 v1, v[70:73] offset:33792
	s_waitcnt vmcnt(12)
	v_cvt_pk_bf16_f32 v70, v30, v34
	v_cvt_pk_bf16_f32 v71, v31, v35
	v_cvt_pk_bf16_f32 v72, v32, v36
	v_cvt_pk_bf16_f32 v73, v33, v37
	ds_write_b128 v1, v[70:73] offset:42240
	s_waitcnt vmcnt(10)
	v_cvt_pk_bf16_f32 v70, v42, v46
	v_cvt_pk_bf16_f32 v71, v43, v47
	v_cvt_pk_bf16_f32 v72, v44, v48
	v_cvt_pk_bf16_f32 v73, v45, v49
	s_and_b64 vcc, exec, s[2:3]
	ds_write_b128 v1, v[70:73] offset:50688
	s_waitcnt vmcnt(8)
	v_cvt_pk_bf16_f32 v70, v58, v62
	v_cvt_pk_bf16_f32 v71, v59, v63
	v_cvt_pk_bf16_f32 v72, v60, v64
	v_cvt_pk_bf16_f32 v73, v61, v65
	ds_write_b128 v1, v[70:73] offset:59136
	s_cbranch_vccnz .LBB0_113
	v_or_b32_e32 v18, s27, v103
	s_ashr_i32 s2, s27, 31
	s_mul_i32 s9, s2, s0
	v_mad_u64_u32 v[18:19], s[2:3], v18, s0, 0
	v_add_u32_e32 v19, s9, v19
	v_lshl_add_u64 v[18:19], v[18:19], 2, s[10:11]
	s_ashr_i32 s9, s8, 31
	v_lshl_add_u64 v[18:19], s[8:9], 2, v[18:19]
	v_lshlrev_b32_e32 v68, 2, v66
	v_lshl_add_u64 v[58:59], v[18:19], 0, v[68:69]
	s_lshl_b32 s2, s0, 5
	s_mov_b32 s3, s1
	v_lshl_add_u64 v[30:31], s[2:3], 2, v[58:59]
	s_mul_i32 s2, s0, 33
	v_lshl_add_u64 v[34:35], s[2:3], 2, v[58:59]
	s_lshl_b32 s2, s0, 6
	v_lshl_add_u64 v[42:43], s[2:3], 2, v[58:59]
	s_mul_i32 s2, s0, 0x41
	v_lshl_add_u64 v[46:47], s[2:3], 2, v[58:59]
	s_mul_i32 s2, s0, 0x60
	v_lshl_add_u64 v[60:61], s[2:3], 2, v[58:59]
	s_mul_i32 s2, s0, 0x61
	v_lshl_add_u64 v[22:23], s[0:1], 2, v[58:59]
	v_lshl_add_u64 v[62:63], s[2:3], 2, v[58:59]
	global_load_dwordx4 v[18:21], v[58:59], off nt
	s_nop 0
	global_load_dwordx4 v[22:25], v[22:23], off nt
	s_nop 0
	global_load_dwordx4 v[30:33], v[30:31], off nt
	s_nop 0
	global_load_dwordx4 v[34:37], v[34:35], off nt
	s_nop 0
	global_load_dwordx4 v[42:45], v[42:43], off nt
	s_nop 0
	global_load_dwordx4 v[46:49], v[46:47], off nt
	s_nop 0
	global_load_dwordx4 v[58:61], v[60:61], off nt
	s_nop 0
	global_load_dwordx4 v[62:65], v[62:63], off nt
.LBB0_113:
	s_mov_b32 s98, 1
	s_waitcnt lgkmcnt(0)
	s_barrier
	s_cmp_eq_u32 s21, 0
	s_mov_b32 s21, 0
	s_cbranch_scc1 .LBB0_117
	s_cmpk_lt_i32 s22, 0x1000
	s_cbranch_scc1 .LBB0_118
	s_cmpk_lt_u32 s22, 0x2000
	s_cbranch_scc1 .LBB0_119
	s_cmpk_lt_u32 s22, 0x2800
	s_cselect_b32 s9, s23, 0xffffd800
	s_cselect_b32 s21, 0, 4
	s_movk_i32 s35, 0x2000
	s_mov_b64 s[2:3], 0
	s_branch .LBB0_120

.LBB0_224:
	ds_read_b128 v[130:133], v208
	ds_read_b128 v[134:137], v208 offset:1024
	ds_read_b128 v[138:141], v208 offset:2048
	ds_read_b128 v[142:145], v208 offset:3072
	ds_read_b128 v[146:149], v209
	ds_read_b128 v[150:153], v209 offset:1024
	ds_read_b128 v[154:157], v209 offset:2048
	ds_read_b128 v[158:161], v209 offset:3072
	s_add_u32 s52, s50, 0xfff00080
	s_addc_u32 s53, s51, -1
	s_cmp_eq_u32 s89, 60
	s_cselect_b32 s55, s43, s53
	s_cselect_b32 s54, s85, s52
	s_cselect_b32 s53, s41, s88
	s_cselect_b32 s52, s86, s87
	v_lshl_add_u64 v[204:205], s[50:51], 0, v[192:193]
	s_add_i32 m0, s56, 0xc000
	ds_read_b128 v[162:165], v210
	ds_read_b128 v[166:169], v210 offset:1024
	ds_read_b128 v[170:173], v210 offset:2048
	ds_read_b128 v[174:177], v210 offset:3072
	ds_read_b128 v[200:203], v210 offset:4096
	ds_read_b128 v[212:215], v210 offset:5120
	ds_read_b128 v[216:219], v210 offset:6144
	ds_read_b128 v[224:227], v210 offset:7168
	global_load_lds_dwordx4 v[204:205], off
	v_lshl_add_u64 v[204:205], s[50:51], 0, v[194:195]
	s_add_i32 m0, s56, 0xe000
	s_nop 0
	global_load_lds_dwordx4 v[204:205], off
	s_waitcnt vmcnt(8)
	s_waitcnt lgkmcnt(0)
	s_setprio 1
	s_barrier
	v_mfma_f32_16x16x32_bf16 v[126:129], v[130:133], v[162:165], v[126:129]
	v_mfma_f32_16x16x32_bf16 v[122:125], v[138:141], v[162:165], v[122:125]
	v_mfma_f32_16x16x32_bf16 v[106:109], v[138:141], v[170:173], v[106:109]
	v_mfma_f32_16x16x32_bf16 v[110:113], v[130:133], v[170:173], v[110:113]
	v_mfma_f32_16x16x32_bf16 v[94:97], v[130:133], v[200:203], v[94:97]
	v_mfma_f32_16x16x32_bf16 v[90:93], v[138:141], v[200:203], v[90:93]
	v_mfma_f32_16x16x32_bf16 v[74:77], v[138:141], v[216:219], v[74:77]
	v_mfma_f32_16x16x32_bf16 v[78:81], v[130:133], v[216:219], v[78:81]
	v_mfma_f32_16x16x32_bf16 v[126:129], v[134:137], v[166:169], v[126:129]
	v_mfma_f32_16x16x32_bf16 v[122:125], v[142:145], v[166:169], v[122:125]
	v_mfma_f32_16x16x32_bf16 v[106:109], v[142:145], v[174:177], v[106:109]
	v_mfma_f32_16x16x32_bf16 v[110:113], v[134:137], v[174:177], v[110:113]
	v_mfma_f32_16x16x32_bf16 v[94:97], v[134:137], v[212:215], v[94:97]
	v_mfma_f32_16x16x32_bf16 v[90:93], v[142:145], v[212:215], v[90:93]
	v_mfma_f32_16x16x32_bf16 v[74:77], v[142:145], v[224:227], v[74:77]
	v_mfma_f32_16x16x32_bf16 v[78:81], v[134:137], v[224:227], v[78:81]
	s_setprio 0
	s_setprio 1
	v_mfma_f32_16x16x32_bf16 v[118:121], v[146:149], v[162:165], v[118:121]
	v_mfma_f32_16x16x32_bf16 v[114:117], v[154:157], v[162:165], v[114:117]
	v_mfma_f32_16x16x32_bf16 v[98:101], v[154:157], v[170:173], v[98:101]
	v_mfma_f32_16x16x32_bf16 v[102:105], v[146:149], v[170:173], v[102:105]
	v_mfma_f32_16x16x32_bf16 v[86:89], v[146:149], v[200:203], v[86:89]
	v_mfma_f32_16x16x32_bf16 v[82:85], v[154:157], v[200:203], v[82:85]
	v_mfma_f32_16x16x32_bf16 v[66:69], v[154:157], v[216:219], v[66:69]
	v_mfma_f32_16x16x32_bf16 v[70:73], v[146:149], v[216:219], v[70:73]
	v_mfma_f32_16x16x32_bf16 v[118:121], v[150:153], v[166:169], v[118:121]
	v_mfma_f32_16x16x32_bf16 v[114:117], v[158:161], v[166:169], v[114:117]
	v_mfma_f32_16x16x32_bf16 v[98:101], v[158:161], v[174:177], v[98:101]
	v_mfma_f32_16x16x32_bf16 v[102:105], v[150:153], v[174:177], v[102:105]
	v_mfma_f32_16x16x32_bf16 v[86:89], v[150:153], v[212:215], v[86:89]
	v_mfma_f32_16x16x32_bf16 v[82:85], v[158:161], v[212:215], v[82:85]
	v_mfma_f32_16x16x32_bf16 v[66:69], v[158:161], v[224:227], v[66:69]
	v_mfma_f32_16x16x32_bf16 v[70:73], v[150:153], v[224:227], v[70:73]
	s_barrier
	s_setprio 0
	s_add_i32 s90, s65, s31
	v_lshl_add_u64 v[204:205], s[52:53], 0, v[182:183]
	s_mov_b32 m0, s90
	ds_read_b128 v[162:165], v210 offset:16384
	ds_read_b128 v[166:169], v210 offset:17408
	ds_read_b128 v[170:173], v210 offset:18432
	ds_read_b128 v[174:177], v210 offset:19456
	ds_read_b128 v[200:203], v210 offset:20480
	ds_read_b128 v[212:215], v210 offset:21504
	ds_read_b128 v[216:219], v210 offset:22528
	ds_read_b128 v[224:227], v210 offset:23552
	global_load_lds_dwordx4 v[204:205], off
	s_add_i32 m0, s90, 0x2000
	s_add_u32 s90, s52, 0x100000
	v_lshl_add_u64 v[220:221], s[52:53], 0, v[178:179]
	s_addc_u32 s91, s53, 0
	s_add_i32 s92, s66, s31
	global_load_lds_dwordx4 v[220:221], off
	v_lshl_add_u64 v[228:229], s[90:91], 0, v[182:183]
	s_mov_b32 m0, s92
	v_lshl_add_u64 v[230:231], s[54:55], 0, v[180:181]
	global_load_lds_dwordx4 v[228:229], off
	v_lshl_add_u64 v[228:229], s[90:91], 0, v[178:179]
	s_add_i32 m0, s92, 0x2000
	s_nop 0
	global_load_lds_dwordx4 v[228:229], off
	v_lshl_add_u64 v[228:229], s[54:55], 0, v[184:185]
	s_mov_b32 m0, s56
	s_nop 0
	global_load_lds_dwordx4 v[228:229], off
	s_mov_b32 m0, s57
	s_nop 0
	global_load_lds_dwordx4 v[230:231], off
	s_waitcnt vmcnt(8)
	s_waitcnt lgkmcnt(0)
	s_setprio 1
	s_barrier
	v_mfma_f32_16x16x32_bf16 v[62:65], v[130:133], v[162:165], v[62:65]
	v_mfma_f32_16x16x32_bf16 v[58:61], v[138:141], v[162:165], v[58:61]
	v_mfma_f32_16x16x32_bf16 v[42:45], v[138:141], v[170:173], v[42:45]
	v_mfma_f32_16x16x32_bf16 v[50:53], v[130:133], v[170:173], v[50:53]
	v_mfma_f32_16x16x32_bf16 v[34:37], v[130:133], v[200:203], v[34:37]
	v_mfma_f32_16x16x32_bf16 v[26:29], v[138:141], v[200:203], v[26:29]
	v_mfma_f32_16x16x32_bf16 v[10:13], v[138:141], v[216:219], v[10:13]
	v_mfma_f32_16x16x32_bf16 v[18:21], v[130:133], v[216:219], v[18:21]
	v_mfma_f32_16x16x32_bf16 v[62:65], v[134:137], v[166:169], v[62:65]
	v_mfma_f32_16x16x32_bf16 v[58:61], v[142:145], v[166:169], v[58:61]
	v_mfma_f32_16x16x32_bf16 v[42:45], v[142:145], v[174:177], v[42:45]
	v_mfma_f32_16x16x32_bf16 v[50:53], v[134:137], v[174:177], v[50:53]
	v_mfma_f32_16x16x32_bf16 v[34:37], v[134:137], v[212:215], v[34:37]
	v_mfma_f32_16x16x32_bf16 v[26:29], v[142:145], v[212:215], v[26:29]
	v_mfma_f32_16x16x32_bf16 v[10:13], v[142:145], v[224:227], v[10:13]
	v_mfma_f32_16x16x32_bf16 v[18:21], v[134:137], v[224:227], v[18:21]
	s_setprio 0
	s_setprio 1
	v_mfma_f32_16x16x32_bf16 v[54:57], v[146:149], v[162:165], v[54:57]
	v_mfma_f32_16x16x32_bf16 v[46:49], v[154:157], v[162:165], v[46:49]
	v_mfma_f32_16x16x32_bf16 v[30:33], v[154:157], v[170:173], v[30:33]
	v_mfma_f32_16x16x32_bf16 v[38:41], v[146:149], v[170:173], v[38:41]
	v_mfma_f32_16x16x32_bf16 v[22:25], v[146:149], v[200:203], v[22:25]
	v_mfma_f32_16x16x32_bf16 v[14:17], v[154:157], v[200:203], v[14:17]
	v_mfma_f32_16x16x32_bf16 v[2:5], v[154:157], v[216:219], v[2:5]
	v_mfma_f32_16x16x32_bf16 v[6:9], v[146:149], v[216:219], v[6:9]
	v_mfma_f32_16x16x32_bf16 v[54:57], v[150:153], v[166:169], v[54:57]
	v_mfma_f32_16x16x32_bf16 v[46:49], v[158:161], v[166:169], v[46:49]
	v_mfma_f32_16x16x32_bf16 v[30:33], v[158:161], v[174:177], v[30:33]
	v_mfma_f32_16x16x32_bf16 v[38:41], v[150:153], v[174:177], v[38:41]
	v_mfma_f32_16x16x32_bf16 v[22:25], v[150:153], v[212:215], v[22:25]
	v_mfma_f32_16x16x32_bf16 v[14:17], v[158:161], v[212:215], v[14:17]
	v_mfma_f32_16x16x32_bf16 v[2:5], v[158:161], v[224:227], v[2:5]
	v_mfma_f32_16x16x32_bf16 v[6:9], v[150:153], v[224:227], v[6:9]
	s_barrier
	s_setprio 0
	s_add_i32 s90, 0, 0x18000
	s_add_i32 s91, 0, 0x1c000
	v_add_u32_e32 v142, s90, v189
	v_add_u32_e32 v158, s91, v189
	ds_read_b128 v[130:133], v142
	ds_read_b128 v[134:137], v142 offset:1024
	ds_read_b128 v[138:141], v142 offset:2048
	ds_read_b128 v[142:145], v142 offset:3072
	ds_read_b128 v[146:149], v158
	ds_read_b128 v[150:153], v158 offset:1024
	ds_read_b128 v[154:157], v158 offset:2048
	ds_read_b128 v[158:161], v158 offset:3072
	s_add_u32 s54, s54, 0x100000
	s_addc_u32 s55, s55, 0
	s_mov_b32 m0, s58
	v_lshl_add_u64 v[232:233], s[54:55], 0, v[184:185]
	ds_read_b128 v[162:165], v210 offset:32768
	ds_read_b128 v[166:169], v210 offset:33792
	ds_read_b128 v[170:173], v210 offset:34816
	ds_read_b128 v[174:177], v210 offset:35840
	ds_read_b128 v[200:203], v210 offset:36864
	ds_read_b128 v[212:215], v210 offset:37888
	ds_read_b128 v[216:219], v210 offset:38912
	ds_read_b128 v[224:227], v210 offset:39936
	global_load_lds_dwordx4 v[232:233], off
	v_lshl_add_u64 v[232:233], s[54:55], 0, v[180:181]
	s_mov_b32 m0, s59
	s_nop 0
	global_load_lds_dwordx4 v[232:233], off
	s_waitcnt vmcnt(8)
	s_waitcnt lgkmcnt(0)
	s_setprio 1
	s_barrier
	v_mfma_f32_16x16x32_bf16 v[126:129], v[130:133], v[162:165], v[126:129]
	v_mfma_f32_16x16x32_bf16 v[122:125], v[138:141], v[162:165], v[122:125]
	v_mfma_f32_16x16x32_bf16 v[106:109], v[138:141], v[170:173], v[106:109]
	v_mfma_f32_16x16x32_bf16 v[110:113], v[130:133], v[170:173], v[110:113]
	v_mfma_f32_16x16x32_bf16 v[94:97], v[130:133], v[200:203], v[94:97]
	v_mfma_f32_16x16x32_bf16 v[90:93], v[138:141], v[200:203], v[90:93]
	v_mfma_f32_16x16x32_bf16 v[74:77], v[138:141], v[216:219], v[74:77]
	v_mfma_f32_16x16x32_bf16 v[78:81], v[130:133], v[216:219], v[78:81]
	v_mfma_f32_16x16x32_bf16 v[126:129], v[134:137], v[166:169], v[126:129]
	v_mfma_f32_16x16x32_bf16 v[122:125], v[142:145], v[166:169], v[122:125]
	v_mfma_f32_16x16x32_bf16 v[106:109], v[142:145], v[174:177], v[106:109]
	v_mfma_f32_16x16x32_bf16 v[110:113], v[134:137], v[174:177], v[110:113]
	v_mfma_f32_16x16x32_bf16 v[94:97], v[134:137], v[212:215], v[94:97]
	v_mfma_f32_16x16x32_bf16 v[90:93], v[142:145], v[212:215], v[90:93]
	v_mfma_f32_16x16x32_bf16 v[74:77], v[142:145], v[224:227], v[74:77]
	v_mfma_f32_16x16x32_bf16 v[78:81], v[134:137], v[224:227], v[78:81]
	s_setprio 0
	s_setprio 1
	v_mfma_f32_16x16x32_bf16 v[118:121], v[146:149], v[162:165], v[118:121]
	v_mfma_f32_16x16x32_bf16 v[114:117], v[154:157], v[162:165], v[114:117]
	v_mfma_f32_16x16x32_bf16 v[98:101], v[154:157], v[170:173], v[98:101]
	v_mfma_f32_16x16x32_bf16 v[102:105], v[146:149], v[170:173], v[102:105]
	v_mfma_f32_16x16x32_bf16 v[86:89], v[146:149], v[200:203], v[86:89]
	v_mfma_f32_16x16x32_bf16 v[82:85], v[154:157], v[200:203], v[82:85]
	v_mfma_f32_16x16x32_bf16 v[66:69], v[154:157], v[216:219], v[66:69]
	v_mfma_f32_16x16x32_bf16 v[70:73], v[146:149], v[216:219], v[70:73]
	v_mfma_f32_16x16x32_bf16 v[118:121], v[150:153], v[166:169], v[118:121]
	v_mfma_f32_16x16x32_bf16 v[114:117], v[158:161], v[166:169], v[114:117]
	v_mfma_f32_16x16x32_bf16 v[98:101], v[158:161], v[174:177], v[98:101]
	v_mfma_f32_16x16x32_bf16 v[102:105], v[150:153], v[174:177], v[102:105]
	v_mfma_f32_16x16x32_bf16 v[86:89], v[150:153], v[212:215], v[86:89]
	v_mfma_f32_16x16x32_bf16 v[82:85], v[158:161], v[212:215], v[82:85]
	v_mfma_f32_16x16x32_bf16 v[66:69], v[158:161], v[224:227], v[66:69]
	v_mfma_f32_16x16x32_bf16 v[70:73], v[150:153], v[224:227], v[70:73]
	s_barrier
	s_setprio 0
	s_add_i32 s54, s90, s31
	v_lshl_add_u64 v[204:205], v[204:205], 0, s[8:9]
	s_mov_b32 m0, s54
	ds_read_b128 v[162:165], v210 offset:49152
	ds_read_b128 v[166:169], v210 offset:50176
	ds_read_b128 v[170:173], v210 offset:51200
	ds_read_b128 v[174:177], v210 offset:52224
	ds_read_b128 v[200:203], v210 offset:53248
	ds_read_b128 v[212:215], v210 offset:54272
	ds_read_b128 v[216:219], v210 offset:55296
	ds_read_b128 v[224:227], v210 offset:56320
	global_load_lds_dwordx4 v[204:205], off
	s_add_i32 m0, s54, 0x2000
	s_add_u32 s52, s52, 0x100080
	v_lshl_add_u64 v[204:205], v[220:221], 0, s[8:9]
	s_addc_u32 s53, s53, 0
	s_add_i32 s54, s91, s31
	global_load_lds_dwordx4 v[204:205], off
	v_lshl_add_u64 v[204:205], s[52:53], 0, v[182:183]
	s_mov_b32 m0, s54
	s_nop 0
	global_load_lds_dwordx4 v[204:205], off
	v_lshl_add_u64 v[204:205], s[52:53], 0, v[178:179]
	s_add_i32 m0, s54, 0x2000
	s_nop 0
	global_load_lds_dwordx4 v[204:205], off
	v_lshl_add_u64 v[204:205], v[228:229], 0, s[8:9]
	s_mov_b32 m0, s62
	s_nop 0
	global_load_lds_dwordx4 v[204:205], off
	v_lshl_add_u64 v[204:205], v[230:231], 0, s[8:9]
	s_mov_b32 m0, s63
	s_nop 0
	global_load_lds_dwordx4 v[204:205], off
	s_waitcnt vmcnt(8)
	s_waitcnt lgkmcnt(0)
	s_setprio 1
	s_barrier
	v_mfma_f32_16x16x32_bf16 v[62:65], v[130:133], v[162:165], v[62:65]
	v_mfma_f32_16x16x32_bf16 v[58:61], v[138:141], v[162:165], v[58:61]
	v_mfma_f32_16x16x32_bf16 v[42:45], v[138:141], v[170:173], v[42:45]
	v_mfma_f32_16x16x32_bf16 v[50:53], v[130:133], v[170:173], v[50:53]
	v_mfma_f32_16x16x32_bf16 v[34:37], v[130:133], v[200:203], v[34:37]
	v_mfma_f32_16x16x32_bf16 v[26:29], v[138:141], v[200:203], v[26:29]
	v_mfma_f32_16x16x32_bf16 v[10:13], v[138:141], v[216:219], v[10:13]
	v_mfma_f32_16x16x32_bf16 v[18:21], v[130:133], v[216:219], v[18:21]
	v_mfma_f32_16x16x32_bf16 v[62:65], v[134:137], v[166:169], v[62:65]
	v_mfma_f32_16x16x32_bf16 v[58:61], v[142:145], v[166:169], v[58:61]
	v_mfma_f32_16x16x32_bf16 v[42:45], v[142:145], v[174:177], v[42:45]
	v_mfma_f32_16x16x32_bf16 v[50:53], v[134:137], v[174:177], v[50:53]
	v_mfma_f32_16x16x32_bf16 v[34:37], v[134:137], v[212:215], v[34:37]
	v_mfma_f32_16x16x32_bf16 v[26:29], v[142:145], v[212:215], v[26:29]
	v_mfma_f32_16x16x32_bf16 v[10:13], v[142:145], v[224:227], v[10:13]
	v_mfma_f32_16x16x32_bf16 v[18:21], v[134:137], v[224:227], v[18:21]
	s_setprio 0
	s_setprio 1
	v_mfma_f32_16x16x32_bf16 v[54:57], v[146:149], v[162:165], v[54:57]
	v_mfma_f32_16x16x32_bf16 v[46:49], v[154:157], v[162:165], v[46:49]
	v_mfma_f32_16x16x32_bf16 v[30:33], v[154:157], v[170:173], v[30:33]
	v_mfma_f32_16x16x32_bf16 v[38:41], v[146:149], v[170:173], v[38:41]
	v_mfma_f32_16x16x32_bf16 v[22:25], v[146:149], v[200:203], v[22:25]
	v_mfma_f32_16x16x32_bf16 v[14:17], v[154:157], v[200:203], v[14:17]
	v_mfma_f32_16x16x32_bf16 v[2:5], v[154:157], v[216:219], v[2:5]
	v_mfma_f32_16x16x32_bf16 v[6:9], v[146:149], v[216:219], v[6:9]
	v_mfma_f32_16x16x32_bf16 v[54:57], v[150:153], v[166:169], v[54:57]
	v_mfma_f32_16x16x32_bf16 v[46:49], v[158:161], v[166:169], v[46:49]
	v_mfma_f32_16x16x32_bf16 v[30:33], v[158:161], v[174:177], v[30:33]
	v_mfma_f32_16x16x32_bf16 v[38:41], v[150:153], v[174:177], v[38:41]
	v_mfma_f32_16x16x32_bf16 v[22:25], v[150:153], v[212:215], v[22:25]
	v_mfma_f32_16x16x32_bf16 v[14:17], v[158:161], v[212:215], v[14:17]
	v_mfma_f32_16x16x32_bf16 v[2:5], v[158:161], v[224:227], v[2:5]
	v_mfma_f32_16x16x32_bf16 v[6:9], v[150:153], v[224:227], v[6:9]
	s_barrier
	s_setprio 0
	s_add_i32 s89, s89, 2
	s_add_u32 s50, s50, 0x100
	s_addc_u32 s51, s51, 0
	s_add_u32 s87, s87, 0x100
	s_addc_u32 s88, s88, 0
	s_cmp_gt_u32 s89, 61
	s_cbranch_scc0 .LBB0_224
	s_and_b64 vcc, exec, s[10:11]
	s_cbranch_vccz .LBB0_229
	s_barrier
	v_lshl_add_u32 v200, s0, 8, v1
	s_cmp_gt_i32 s84, 15
	s_mov_b64 s[50:51], -1
	s_cbranch_scc1 .LBB0_230

.LBB0_426:
	s_add_u32 s4, s74, 0x13000000
	s_addc_u32 s5, s75, 0
	s_add_u32 s10, s74, 0x8400000
	s_addc_u32 s11, s75, 0
	v_lshlrev_b32_e32 v66, 2, v0
	s_add_u32 s16, s74, 0x6400000
	v_lshrrev_b32_e32 v1, 5, v0
	v_and_b32_e32 v66, 0x7c, v66
	s_addc_u32 s17, s75, 0
	v_mul_u32_u24_e32 v1, 0x210, v1
	v_lshlrev_b32_e32 v67, 2, v66
	s_add_u32 s18, s74, 0x400000
	v_add3_u32 v1, 0, v1, v67
	s_addc_u32 s19, s75, 0
	v_lshrrev_b32_e32 v67, 4, v0
	s_add_i32 s2, s8, 0
	s_movk_i32 s0, 0x210
	s_mov_b32 s1, 0
	v_and_b32_e32 v67, 30, v67
	v_mov_b32_e32 v68, s2
	v_mov_b32_e32 v69, 0
	v_mad_u32_u24 v102, v222, s0, v68
	v_or_b32_e32 v103, 0x80, v67
	s_mov_b64 s[22:23], 0
	s_movk_i32 s8, 0xe000
	s_mov_b32 s13, s78
	s_mov_b32 s38, s1
	s_mov_b32 s34, 0
	s_mov_b32 s15, 0
	s_mov_b32 s0, s1
	s_mov_b32 s30, s1
	s_mov_b64 s[20:21], 0
	s_mov_b32 s98, 0
	s_branch .LBB0_428
.Lcvb_steady:
	s_waitcnt vmcnt(46)
	v_cvt_pk_bf16_f32 v70, v6, v2
	v_cvt_pk_bf16_f32 v71, v7, v3
	v_cvt_pk_bf16_f32 v72, v8, v4
	v_cvt_pk_bf16_f32 v73, v9, v5
	ds_write_b128 v1, v[70:73]
	s_waitcnt vmcnt(44)
	v_cvt_pk_bf16_f32 v70, v14, v10
	v_cvt_pk_bf16_f32 v71, v15, v11
	v_cvt_pk_bf16_f32 v72, v16, v12
	v_cvt_pk_bf16_f32 v73, v17, v13
	v_cndmask_b32_e64 v68, 0, 1, s[44:45]
	ds_write_b128 v1, v[70:73] offset:8448
	s_waitcnt vmcnt(42)
	v_cvt_pk_bf16_f32 v70, v22, v18
	v_cvt_pk_bf16_f32 v71, v23, v19
	v_cvt_pk_bf16_f32 v72, v24, v20
	v_cvt_pk_bf16_f32 v73, v25, v21
	v_cmp_ne_u32_e64 s[2:3], 1, v68
	s_andn2_b64 vcc, exec, s[44:45]
	ds_write_b128 v1, v[70:73] offset:16896
	s_waitcnt vmcnt(40)
	v_cvt_pk_bf16_f32 v70, v30, v26
	v_cvt_pk_bf16_f32 v71, v31, v27
	v_cvt_pk_bf16_f32 v72, v32, v28
	v_cvt_pk_bf16_f32 v73, v33, v29
	ds_write_b128 v1, v[70:73] offset:25344
	s_cbranch_vccnz .Lcvb_snomore
	v_or_b32_e32 v2, s34, v67
	s_ashr_i32 s35, s34, 31
	s_mul_i32 s35, s35, s0
	v_mad_u64_u32 v[2:3], s[44:45], v2, s0, 0
	v_add_u32_e32 v3, s35, v3
	v_lshl_add_u64 v[2:3], v[2:3], 2, s[20:21]
	s_ashr_i32 s39, s38, 31
	v_lshl_add_u64 v[2:3], s[38:39], 2, v[2:3]
	v_lshlrev_b32_e32 v68, 2, v66
	v_lshl_add_u64 v[26:27], v[2:3], 0, v[68:69]
	s_lshl_b32 s44, s0, 5
	s_mov_b32 s45, s1
	v_lshl_add_u64 v[10:11], s[44:45], 2, v[26:27]
	s_mul_i32 s44, s0, 33
	v_lshl_add_u64 v[12:13], s[44:45], 2, v[26:27]
	s_lshl_b32 s44, s0, 6
	v_lshl_add_u64 v[18:19], s[44:45], 2, v[26:27]
	s_mul_i32 s44, s0, 0x41
	v_lshl_add_u64 v[20:21], s[44:45], 2, v[26:27]
	s_mul_i32 s44, s0, 0x60
	v_lshl_add_u64 v[2:3], s[0:1], 2, v[26:27]
	v_lshl_add_u64 v[28:29], s[44:45], 2, v[26:27]
	s_mul_i32 s44, s0, 0x61
	global_load_dwordx4 v[6:9], v[26:27], off nt
	s_nop 0
	global_load_dwordx4 v[2:5], v[2:3], off nt
	v_lshl_add_u64 v[26:27], s[44:45], 2, v[26:27]
	global_load_dwordx4 v[14:17], v[10:11], off nt
	s_nop 0
	global_load_dwordx4 v[10:13], v[12:13], off nt
	s_nop 0
	global_load_dwordx4 v[22:25], v[18:19], off nt
	s_nop 0
	global_load_dwordx4 v[18:21], v[20:21], off nt
	s_nop 0
	global_load_dwordx4 v[30:33], v[28:29], off nt
	s_nop 0
	global_load_dwordx4 v[26:29], v[26:27], off nt
.Lcvb_smid:
	s_waitcnt vmcnt(46)
	v_cvt_pk_bf16_f32 v70, v34, v38
	v_cvt_pk_bf16_f32 v71, v35, v39
	v_cvt_pk_bf16_f32 v72, v36, v40
	v_cvt_pk_bf16_f32 v73, v37, v41
	ds_write_b128 v1, v[70:73] offset:33792
	s_waitcnt vmcnt(44)
	v_cvt_pk_bf16_f32 v70, v42, v46
	v_cvt_pk_bf16_f32 v71, v43, v47
	v_cvt_pk_bf16_f32 v72, v44, v48
	v_cvt_pk_bf16_f32 v73, v45, v49
	ds_write_b128 v1, v[70:73] offset:42240
	s_waitcnt vmcnt(42)
	v_cvt_pk_bf16_f32 v70, v50, v54
	v_cvt_pk_bf16_f32 v71, v51, v55
	v_cvt_pk_bf16_f32 v72, v52, v56
	v_cvt_pk_bf16_f32 v73, v53, v57
	s_and_b64 vcc, exec, s[2:3]
	ds_write_b128 v1, v[70:73] offset:50688
	s_waitcnt vmcnt(40)
	v_cvt_pk_bf16_f32 v70, v58, v62
	v_cvt_pk_bf16_f32 v71, v59, v63
	v_cvt_pk_bf16_f32 v72, v60, v64
	v_cvt_pk_bf16_f32 v73, v61, v65
	ds_write_b128 v1, v[70:73] offset:59136
	s_cbranch_vccnz .LBB0_446
	v_or_b32_e32 v34, s34, v103
	s_ashr_i32 s2, s34, 31
	s_mul_i32 s35, s2, s0
	v_mad_u64_u32 v[34:35], s[2:3], v34, s0, 0
	v_add_u32_e32 v35, s35, v35
	v_lshl_add_u64 v[34:35], v[34:35], 2, s[20:21]
	s_ashr_i32 s39, s38, 31
	v_lshl_add_u64 v[34:35], s[38:39], 2, v[34:35]
	v_lshlrev_b32_e32 v68, 2, v66
	v_lshl_add_u64 v[58:59], v[34:35], 0, v[68:69]
	s_lshl_b32 s2, s0, 5
	s_mov_b32 s3, s1
	v_lshl_add_u64 v[42:43], s[2:3], 2, v[58:59]
	s_mul_i32 s2, s0, 33
	v_lshl_add_u64 v[46:47], s[2:3], 2, v[58:59]
	s_lshl_b32 s2, s0, 6
	v_lshl_add_u64 v[50:51], s[2:3], 2, v[58:59]
	s_mul_i32 s2, s0, 0x41
	v_lshl_add_u64 v[54:55], s[2:3], 2, v[58:59]
	s_mul_i32 s2, s0, 0x60
	v_lshl_add_u64 v[60:61], s[2:3], 2, v[58:59]
	s_mul_i32 s2, s0, 0x61
	v_lshl_add_u64 v[38:39], s[0:1], 2, v[58:59]
	v_lshl_add_u64 v[62:63], s[2:3], 2, v[58:59]
	global_load_dwordx4 v[34:37], v[58:59], off nt
	s_nop 0
	global_load_dwordx4 v[38:41], v[38:39], off nt
	s_nop 0
	global_load_dwordx4 v[42:45], v[42:43], off nt
	s_nop 0
	global_load_dwordx4 v[46:49], v[46:47], off nt
	s_nop 0
	global_load_dwordx4 v[50:53], v[50:51], off nt
	s_nop 0
	global_load_dwordx4 v[54:57], v[54:55], off nt
	s_nop 0
	global_load_dwordx4 v[58:61], v[60:61], off nt
	s_nop 0
	global_load_dwordx4 v[62:65], v[62:63], off nt
	s_branch .LBB0_446

.LBB0_442:
	s_cmp_lg_u32 s98, 0
	s_cbranch_scc1 .Lcvb_steady
	s_waitcnt vmcnt(14)
	v_cvt_pk_bf16_f32 v70, v6, v2
	v_cvt_pk_bf16_f32 v71, v7, v3
	v_cvt_pk_bf16_f32 v72, v8, v4
	v_cvt_pk_bf16_f32 v73, v9, v5
	ds_write_b128 v1, v[70:73]
	s_waitcnt vmcnt(12)
	v_cvt_pk_bf16_f32 v70, v14, v10
	v_cvt_pk_bf16_f32 v71, v15, v11
	v_cvt_pk_bf16_f32 v72, v16, v12
	v_cvt_pk_bf16_f32 v73, v17, v13
	v_cndmask_b32_e64 v68, 0, 1, s[44:45]
	ds_write_b128 v1, v[70:73] offset:8448
	s_waitcnt vmcnt(10)
	v_cvt_pk_bf16_f32 v70, v22, v18
	v_cvt_pk_bf16_f32 v71, v23, v19
	v_cvt_pk_bf16_f32 v72, v24, v20
	v_cvt_pk_bf16_f32 v73, v25, v21
	v_cmp_ne_u32_e64 s[2:3], 1, v68
	s_andn2_b64 vcc, exec, s[44:45]
	ds_write_b128 v1, v[70:73] offset:16896
	s_waitcnt vmcnt(8)
	v_cvt_pk_bf16_f32 v70, v30, v26
	v_cvt_pk_bf16_f32 v71, v31, v27
	v_cvt_pk_bf16_f32 v72, v32, v28
	v_cvt_pk_bf16_f32 v73, v33, v29
	ds_write_b128 v1, v[70:73] offset:25344
	s_cbranch_vccnz .Lcvb_fnomore
	v_or_b32_e32 v2, s34, v67
	s_ashr_i32 s35, s34, 31
	s_mul_i32 s35, s35, s0
	v_mad_u64_u32 v[2:3], s[44:45], v2, s0, 0
	v_add_u32_e32 v3, s35, v3
	v_lshl_add_u64 v[2:3], v[2:3], 2, s[20:21]
	s_ashr_i32 s39, s38, 31
	v_lshl_add_u64 v[2:3], s[38:39], 2, v[2:3]
	v_lshlrev_b32_e32 v68, 2, v66
	v_lshl_add_u64 v[26:27], v[2:3], 0, v[68:69]
	s_lshl_b32 s44, s0, 5
	s_mov_b32 s45, s1
	v_lshl_add_u64 v[10:11], s[44:45], 2, v[26:27]
	s_mul_i32 s44, s0, 33
	v_lshl_add_u64 v[12:13], s[44:45], 2, v[26:27]
	s_lshl_b32 s44, s0, 6
	v_lshl_add_u64 v[18:19], s[44:45], 2, v[26:27]
	s_mul_i32 s44, s0, 0x41
	v_lshl_add_u64 v[20:21], s[44:45], 2, v[26:27]
	s_mul_i32 s44, s0, 0x60
	v_lshl_add_u64 v[2:3], s[0:1], 2, v[26:27]
	v_lshl_add_u64 v[28:29], s[44:45], 2, v[26:27]
	s_mul_i32 s44, s0, 0x61
	global_load_dwordx4 v[6:9], v[26:27], off nt
	s_nop 0
	global_load_dwordx4 v[2:5], v[2:3], off nt
	v_lshl_add_u64 v[26:27], s[44:45], 2, v[26:27]
	global_load_dwordx4 v[14:17], v[10:11], off nt
	s_nop 0
	global_load_dwordx4 v[10:13], v[12:13], off nt
	s_nop 0
	global_load_dwordx4 v[22:25], v[18:19], off nt
	s_nop 0
	global_load_dwordx4 v[18:21], v[20:21], off nt
	s_nop 0
	global_load_dwordx4 v[30:33], v[28:29], off nt
	s_nop 0
	global_load_dwordx4 v[26:29], v[26:27], off nt
.LBB0_444:
	s_waitcnt vmcnt(14)
	v_cvt_pk_bf16_f32 v70, v34, v38
	v_cvt_pk_bf16_f32 v71, v35, v39
	v_cvt_pk_bf16_f32 v72, v36, v40
	v_cvt_pk_bf16_f32 v73, v37, v41
	ds_write_b128 v1, v[70:73] offset:33792
	s_waitcnt vmcnt(12)
	v_cvt_pk_bf16_f32 v70, v42, v46
	v_cvt_pk_bf16_f32 v71, v43, v47
	v_cvt_pk_bf16_f32 v72, v44, v48
	v_cvt_pk_bf16_f32 v73, v45, v49
	ds_write_b128 v1, v[70:73] offset:42240
	s_waitcnt vmcnt(10)
	v_cvt_pk_bf16_f32 v70, v50, v54
	v_cvt_pk_bf16_f32 v71, v51, v55
	v_cvt_pk_bf16_f32 v72, v52, v56
	v_cvt_pk_bf16_f32 v73, v53, v57
	s_and_b64 vcc, exec, s[2:3]
	ds_write_b128 v1, v[70:73] offset:50688
	s_waitcnt vmcnt(8)
	v_cvt_pk_bf16_f32 v70, v58, v62
	v_cvt_pk_bf16_f32 v71, v59, v63
	v_cvt_pk_bf16_f32 v72, v60, v64
	v_cvt_pk_bf16_f32 v73, v61, v65
	ds_write_b128 v1, v[70:73] offset:59136
	s_cbranch_vccnz .LBB0_446
	v_or_b32_e32 v34, s34, v103
	s_ashr_i32 s2, s34, 31
	s_mul_i32 s35, s2, s0
	v_mad_u64_u32 v[34:35], s[2:3], v34, s0, 0
	v_add_u32_e32 v35, s35, v35
	v_lshl_add_u64 v[34:35], v[34:35], 2, s[20:21]
	s_ashr_i32 s39, s38, 31
	v_lshl_add_u64 v[34:35], s[38:39], 2, v[34:35]
	v_lshlrev_b32_e32 v68, 2, v66
	v_lshl_add_u64 v[58:59], v[34:35], 0, v[68:69]
	s_lshl_b32 s2, s0, 5
	s_mov_b32 s3, s1
	v_lshl_add_u64 v[42:43], s[2:3], 2, v[58:59]
	s_mul_i32 s2, s0, 33
	v_lshl_add_u64 v[46:47], s[2:3], 2, v[58:59]
	s_lshl_b32 s2, s0, 6
	v_lshl_add_u64 v[50:51], s[2:3], 2, v[58:59]
	s_mul_i32 s2, s0, 0x41
	v_lshl_add_u64 v[54:55], s[2:3], 2, v[58:59]
	s_mul_i32 s2, s0, 0x60
	v_lshl_add_u64 v[60:61], s[2:3], 2, v[58:59]
	s_mul_i32 s2, s0, 0x61
	v_lshl_add_u64 v[38:39], s[0:1], 2, v[58:59]
	v_lshl_add_u64 v[62:63], s[2:3], 2, v[58:59]
	global_load_dwordx4 v[34:37], v[58:59], off nt
	s_nop 0
	global_load_dwordx4 v[38:41], v[38:39], off nt
	s_nop 0
	global_load_dwordx4 v[42:45], v[42:43], off nt
	s_nop 0
	global_load_dwordx4 v[46:49], v[46:47], off nt
	s_nop 0
	global_load_dwordx4 v[50:53], v[50:51], off nt
	s_nop 0
	global_load_dwordx4 v[54:57], v[54:55], off nt
	s_nop 0
	global_load_dwordx4 v[58:61], v[60:61], off nt
	s_nop 0
	global_load_dwordx4 v[62:65], v[62:63], off nt
.LBB0_446:
	s_mov_b32 s98, 1
	s_waitcnt lgkmcnt(0)
	s_barrier
	s_cmp_lt_i32 s31, 1
	s_cbranch_scc1 .LBB0_451
	s_cmp_eq_u32 s31, 1
	s_mov_b64 s[48:49], -1
	s_cbranch_scc0 .LBB0_453
	s_cmpk_lt_i32 s42, 0x1000
	s_mov_b64 s[48:49], 0
	s_cbranch_scc1 .LBB0_452
	s_cmpk_lt_u32 s42, 0x2000
	s_cbranch_scc1 .LBB0_489
	s_cmpk_lt_u32 s42, 0x2800
	s_cselect_b32 s43, 0, 4
	s_cselect_b32 s35, s8, 0xffffd800
	s_movk_i32 s41, 0x2000
	s_mov_b64 s[2:3], 0
	s_mov_b64 s[44:45], 0
	s_branch .LBB0_455

.LBB0_672:
	v_add_u32_e32 v142, s51, v220
	v_add_u32_e32 v158, s81, v220
	ds_read_b128 v[130:133], v142
	ds_read_b128 v[134:137], v142 offset:1024
	ds_read_b128 v[138:141], v142 offset:2048
	ds_read_b128 v[142:145], v142 offset:3072
	ds_read_b128 v[146:149], v158
	ds_read_b128 v[150:153], v158 offset:1024
	ds_read_b128 v[154:157], v158 offset:2048
	ds_read_b128 v[158:161], v158 offset:3072
	s_add_u32 s16, s0, 0xfff00080
	s_addc_u32 s17, s1, -1
	s_cmp_eq_u32 s26, 60
	s_cselect_b32 s19, s20, s17
	s_cselect_b32 s18, s21, s16
	s_cselect_b32 s17, s22, s25
	s_cselect_b32 s16, s23, s24
	v_lshl_add_u64 v[218:219], s[0:1], 0, v[194:195]
	s_add_i32 m0, s31, 0xc000
	ds_read_b128 v[162:165], v233
	ds_read_b128 v[166:169], v233 offset:1024
	ds_read_b128 v[170:173], v233 offset:2048
	ds_read_b128 v[174:177], v233 offset:3072
	ds_read_b128 v[202:205], v233 offset:4096
	ds_read_b128 v[206:209], v233 offset:5120
	ds_read_b128 v[210:213], v233 offset:6144
	ds_read_b128 v[214:217], v233 offset:7168
	global_load_lds_dwordx4 v[218:219], off
	v_lshl_add_u64 v[218:219], s[0:1], 0, v[196:197]
	s_add_i32 m0, s31, 0xe000
	s_nop 0
	global_load_lds_dwordx4 v[218:219], off
	s_waitcnt vmcnt(8)
	s_waitcnt lgkmcnt(0)
	s_setprio 1
	s_barrier
	v_mfma_f32_16x16x32_bf16 v[90:93], v[130:133], v[162:165], v[90:93]
	v_mfma_f32_16x16x32_bf16 v[58:61], v[138:141], v[162:165], v[58:61]
	v_mfma_f32_16x16x32_bf16 v[66:69], v[138:141], v[170:173], v[66:69]
	v_mfma_f32_16x16x32_bf16 v[98:101], v[130:133], v[170:173], v[98:101]
	v_mfma_f32_16x16x32_bf16 v[102:105], v[130:133], v[202:205], v[102:105]
	v_mfma_f32_16x16x32_bf16 v[70:73], v[138:141], v[202:205], v[70:73]
	v_mfma_f32_16x16x32_bf16 v[78:81], v[138:141], v[210:213], v[78:81]
	v_mfma_f32_16x16x32_bf16 v[110:113], v[130:133], v[210:213], v[110:113]
	v_mfma_f32_16x16x32_bf16 v[90:93], v[134:137], v[166:169], v[90:93]
	v_mfma_f32_16x16x32_bf16 v[58:61], v[142:145], v[166:169], v[58:61]
	v_mfma_f32_16x16x32_bf16 v[66:69], v[142:145], v[174:177], v[66:69]
	v_mfma_f32_16x16x32_bf16 v[98:101], v[134:137], v[174:177], v[98:101]
	v_mfma_f32_16x16x32_bf16 v[102:105], v[134:137], v[206:209], v[102:105]
	v_mfma_f32_16x16x32_bf16 v[70:73], v[142:145], v[206:209], v[70:73]
	v_mfma_f32_16x16x32_bf16 v[78:81], v[142:145], v[214:217], v[78:81]
	v_mfma_f32_16x16x32_bf16 v[110:113], v[134:137], v[214:217], v[110:113]
	s_setprio 0
	s_setprio 1
	v_mfma_f32_16x16x32_bf16 v[26:29], v[146:149], v[162:165], v[26:29]
	v_mfma_f32_16x16x32_bf16 v[2:5], v[154:157], v[162:165], v[2:5]
	v_mfma_f32_16x16x32_bf16 v[6:9], v[154:157], v[170:173], v[6:9]
	v_mfma_f32_16x16x32_bf16 v[34:37], v[146:149], v[170:173], v[34:37]
	v_mfma_f32_16x16x32_bf16 v[38:41], v[146:149], v[202:205], v[38:41]
	v_mfma_f32_16x16x32_bf16 v[10:13], v[154:157], v[202:205], v[10:13]
	v_mfma_f32_16x16x32_bf16 v[14:17], v[154:157], v[210:213], v[14:17]
	v_mfma_f32_16x16x32_bf16 v[46:49], v[146:149], v[210:213], v[46:49]
	v_mfma_f32_16x16x32_bf16 v[26:29], v[150:153], v[166:169], v[26:29]
	v_mfma_f32_16x16x32_bf16 v[2:5], v[158:161], v[166:169], v[2:5]
	v_mfma_f32_16x16x32_bf16 v[6:9], v[158:161], v[174:177], v[6:9]
	v_mfma_f32_16x16x32_bf16 v[34:37], v[150:153], v[174:177], v[34:37]
	v_mfma_f32_16x16x32_bf16 v[38:41], v[150:153], v[206:209], v[38:41]
	v_mfma_f32_16x16x32_bf16 v[10:13], v[158:161], v[206:209], v[10:13]
	v_mfma_f32_16x16x32_bf16 v[14:17], v[158:161], v[214:217], v[14:17]
	v_mfma_f32_16x16x32_bf16 v[46:49], v[150:153], v[214:217], v[46:49]
	s_barrier
	s_setprio 0
	s_add_i32 s27, s51, s15
	v_lshl_add_u64 v[218:219], s[16:17], 0, v[178:179]
	s_mov_b32 m0, s27
	ds_read_b128 v[162:165], v233 offset:16384
	ds_read_b128 v[166:169], v233 offset:17408
	ds_read_b128 v[170:173], v233 offset:18432
	ds_read_b128 v[174:177], v233 offset:19456
	ds_read_b128 v[202:205], v233 offset:20480
	ds_read_b128 v[206:209], v233 offset:21504
	ds_read_b128 v[210:213], v233 offset:22528
	ds_read_b128 v[214:217], v233 offset:23552
	global_load_lds_dwordx4 v[218:219], off
	s_add_i32 m0, s27, 0x2000
	s_add_u32 s62, s16, 0x100000
	v_lshl_add_u64 v[242:243], s[16:17], 0, v[180:181]
	s_addc_u32 s63, s17, 0
	s_add_i32 s27, s81, s15
	global_load_lds_dwordx4 v[242:243], off
	v_lshl_add_u64 v[244:245], s[62:63], 0, v[178:179]
	s_mov_b32 m0, s27
	v_lshl_add_u64 v[246:247], s[18:19], 0, v[180:181]
	global_load_lds_dwordx4 v[244:245], off
	v_lshl_add_u64 v[244:245], s[62:63], 0, v[180:181]
	s_add_i32 m0, s27, 0x2000
	s_nop 0
	global_load_lds_dwordx4 v[244:245], off
	v_lshl_add_u64 v[244:245], s[18:19], 0, v[178:179]
	s_mov_b32 m0, s31
	s_nop 0
	global_load_lds_dwordx4 v[244:245], off
	s_mov_b32 m0, s34
	s_nop 0
	global_load_lds_dwordx4 v[246:247], off
	s_waitcnt vmcnt(8)
	s_waitcnt lgkmcnt(0)
	s_setprio 1
	s_barrier
	v_mfma_f32_16x16x32_bf16 v[114:117], v[130:133], v[162:165], v[114:117]
	v_mfma_f32_16x16x32_bf16 v[82:85], v[138:141], v[162:165], v[82:85]
	v_mfma_f32_16x16x32_bf16 v[86:89], v[138:141], v[170:173], v[86:89]
	v_mfma_f32_16x16x32_bf16 v[118:121], v[130:133], v[170:173], v[118:121]
	v_mfma_f32_16x16x32_bf16 v[122:125], v[130:133], v[202:205], v[122:125]
	v_mfma_f32_16x16x32_bf16 v[94:97], v[138:141], v[202:205], v[94:97]
	v_mfma_f32_16x16x32_bf16 v[106:109], v[138:141], v[210:213], v[106:109]
	v_mfma_f32_16x16x32_bf16 v[126:129], v[130:133], v[210:213], v[126:129]
	v_mfma_f32_16x16x32_bf16 v[114:117], v[134:137], v[166:169], v[114:117]
	v_mfma_f32_16x16x32_bf16 v[82:85], v[142:145], v[166:169], v[82:85]
	v_mfma_f32_16x16x32_bf16 v[86:89], v[142:145], v[174:177], v[86:89]
	v_mfma_f32_16x16x32_bf16 v[118:121], v[134:137], v[174:177], v[118:121]
	v_mfma_f32_16x16x32_bf16 v[122:125], v[134:137], v[206:209], v[122:125]
	v_mfma_f32_16x16x32_bf16 v[94:97], v[142:145], v[206:209], v[94:97]
	v_mfma_f32_16x16x32_bf16 v[106:109], v[142:145], v[214:217], v[106:109]
	v_mfma_f32_16x16x32_bf16 v[126:129], v[134:137], v[214:217], v[126:129]
	s_setprio 0
	s_setprio 1
	v_mfma_f32_16x16x32_bf16 v[50:53], v[146:149], v[162:165], v[50:53]
	v_mfma_f32_16x16x32_bf16 v[18:21], v[154:157], v[162:165], v[18:21]
	v_mfma_f32_16x16x32_bf16 v[22:25], v[154:157], v[170:173], v[22:25]
	v_mfma_f32_16x16x32_bf16 v[54:57], v[146:149], v[170:173], v[54:57]
	v_mfma_f32_16x16x32_bf16 v[62:65], v[146:149], v[202:205], v[62:65]
	v_mfma_f32_16x16x32_bf16 v[30:33], v[154:157], v[202:205], v[30:33]
	v_mfma_f32_16x16x32_bf16 v[42:45], v[154:157], v[210:213], v[42:45]
	v_mfma_f32_16x16x32_bf16 v[74:77], v[146:149], v[210:213], v[74:77]
	v_mfma_f32_16x16x32_bf16 v[50:53], v[150:153], v[166:169], v[50:53]
	v_mfma_f32_16x16x32_bf16 v[18:21], v[158:161], v[166:169], v[18:21]
	v_mfma_f32_16x16x32_bf16 v[22:25], v[158:161], v[174:177], v[22:25]
	v_mfma_f32_16x16x32_bf16 v[54:57], v[150:153], v[174:177], v[54:57]
	v_mfma_f32_16x16x32_bf16 v[62:65], v[150:153], v[206:209], v[62:65]
	v_mfma_f32_16x16x32_bf16 v[30:33], v[158:161], v[206:209], v[30:33]
	v_mfma_f32_16x16x32_bf16 v[42:45], v[158:161], v[214:217], v[42:45]
	v_mfma_f32_16x16x32_bf16 v[74:77], v[150:153], v[214:217], v[74:77]
	s_barrier
	s_setprio 0
	s_add_i32 s27, 0, 0x18000
	s_add_i32 s59, 0, 0x1c000
	v_add_u32_e32 v142, s27, v220
	v_add_u32_e32 v158, s59, v220
	ds_read_b128 v[130:133], v142
	ds_read_b128 v[134:137], v142 offset:1024
	ds_read_b128 v[138:141], v142 offset:2048
	ds_read_b128 v[142:145], v142 offset:3072
	ds_read_b128 v[146:149], v158
	ds_read_b128 v[150:153], v158 offset:1024
	ds_read_b128 v[154:157], v158 offset:2048
	ds_read_b128 v[158:161], v158 offset:3072
	s_add_u32 s18, s18, 0x100000
	s_addc_u32 s19, s19, 0
	s_mov_b32 m0, s35
	v_lshl_add_u64 v[248:249], s[18:19], 0, v[178:179]
	ds_read_b128 v[162:165], v233 offset:32768
	ds_read_b128 v[166:169], v233 offset:33792
	ds_read_b128 v[170:173], v233 offset:34816
	ds_read_b128 v[174:177], v233 offset:35840
	ds_read_b128 v[202:205], v233 offset:36864
	ds_read_b128 v[206:209], v233 offset:37888
	ds_read_b128 v[210:213], v233 offset:38912
	ds_read_b128 v[214:217], v233 offset:39936
	global_load_lds_dwordx4 v[248:249], off
	v_lshl_add_u64 v[248:249], s[18:19], 0, v[180:181]
	s_mov_b32 m0, s86
	s_nop 0
	global_load_lds_dwordx4 v[248:249], off
	s_waitcnt vmcnt(8)
	s_waitcnt lgkmcnt(0)
	s_setprio 1
	s_barrier
	v_mfma_f32_16x16x32_bf16 v[90:93], v[130:133], v[162:165], v[90:93]
	v_mfma_f32_16x16x32_bf16 v[58:61], v[138:141], v[162:165], v[58:61]
	v_mfma_f32_16x16x32_bf16 v[66:69], v[138:141], v[170:173], v[66:69]
	v_mfma_f32_16x16x32_bf16 v[98:101], v[130:133], v[170:173], v[98:101]
	v_mfma_f32_16x16x32_bf16 v[102:105], v[130:133], v[202:205], v[102:105]
	v_mfma_f32_16x16x32_bf16 v[70:73], v[138:141], v[202:205], v[70:73]
	v_mfma_f32_16x16x32_bf16 v[78:81], v[138:141], v[210:213], v[78:81]
	v_mfma_f32_16x16x32_bf16 v[110:113], v[130:133], v[210:213], v[110:113]
	v_mfma_f32_16x16x32_bf16 v[90:93], v[134:137], v[166:169], v[90:93]
	v_mfma_f32_16x16x32_bf16 v[58:61], v[142:145], v[166:169], v[58:61]
	v_mfma_f32_16x16x32_bf16 v[66:69], v[142:145], v[174:177], v[66:69]
	v_mfma_f32_16x16x32_bf16 v[98:101], v[134:137], v[174:177], v[98:101]
	v_mfma_f32_16x16x32_bf16 v[102:105], v[134:137], v[206:209], v[102:105]
	v_mfma_f32_16x16x32_bf16 v[70:73], v[142:145], v[206:209], v[70:73]
	v_mfma_f32_16x16x32_bf16 v[78:81], v[142:145], v[214:217], v[78:81]
	v_mfma_f32_16x16x32_bf16 v[110:113], v[134:137], v[214:217], v[110:113]
	s_setprio 0
	s_setprio 1
	v_mfma_f32_16x16x32_bf16 v[26:29], v[146:149], v[162:165], v[26:29]
	v_mfma_f32_16x16x32_bf16 v[2:5], v[154:157], v[162:165], v[2:5]
	v_mfma_f32_16x16x32_bf16 v[6:9], v[154:157], v[170:173], v[6:9]
	v_mfma_f32_16x16x32_bf16 v[34:37], v[146:149], v[170:173], v[34:37]
	v_mfma_f32_16x16x32_bf16 v[38:41], v[146:149], v[202:205], v[38:41]
	v_mfma_f32_16x16x32_bf16 v[10:13], v[154:157], v[202:205], v[10:13]
	v_mfma_f32_16x16x32_bf16 v[14:17], v[154:157], v[210:213], v[14:17]
	v_mfma_f32_16x16x32_bf16 v[46:49], v[146:149], v[210:213], v[46:49]
	v_mfma_f32_16x16x32_bf16 v[26:29], v[150:153], v[166:169], v[26:29]
	v_mfma_f32_16x16x32_bf16 v[2:5], v[158:161], v[166:169], v[2:5]
	v_mfma_f32_16x16x32_bf16 v[6:9], v[158:161], v[174:177], v[6:9]
	v_mfma_f32_16x16x32_bf16 v[34:37], v[150:153], v[174:177], v[34:37]
	v_mfma_f32_16x16x32_bf16 v[38:41], v[150:153], v[206:209], v[38:41]
	v_mfma_f32_16x16x32_bf16 v[10:13], v[158:161], v[206:209], v[10:13]
	v_mfma_f32_16x16x32_bf16 v[14:17], v[158:161], v[214:217], v[14:17]
	v_mfma_f32_16x16x32_bf16 v[46:49], v[150:153], v[214:217], v[46:49]
	s_barrier
	s_setprio 0
	s_add_i32 s18, s27, s15
	v_lshl_add_u64 v[218:219], v[218:219], 0, s[44:45]
	s_mov_b32 m0, s18
	ds_read_b128 v[162:165], v233 offset:49152
	ds_read_b128 v[166:169], v233 offset:50176
	ds_read_b128 v[170:173], v233 offset:51200
	ds_read_b128 v[174:177], v233 offset:52224
	ds_read_b128 v[202:205], v233 offset:53248
	ds_read_b128 v[206:209], v233 offset:54272
	ds_read_b128 v[210:213], v233 offset:55296
	ds_read_b128 v[214:217], v233 offset:56320
	global_load_lds_dwordx4 v[218:219], off
	s_add_i32 m0, s18, 0x2000
	s_add_u32 s16, s16, 0x100080
	v_lshl_add_u64 v[218:219], v[242:243], 0, s[44:45]
	s_addc_u32 s17, s17, 0
	s_add_i32 s18, s59, s15
	global_load_lds_dwordx4 v[218:219], off
	v_lshl_add_u64 v[218:219], s[16:17], 0, v[178:179]
	s_mov_b32 m0, s18
	s_nop 0
	global_load_lds_dwordx4 v[218:219], off
	v_lshl_add_u64 v[218:219], s[16:17], 0, v[180:181]
	s_add_i32 m0, s18, 0x2000
	s_nop 0
	global_load_lds_dwordx4 v[218:219], off
	v_lshl_add_u64 v[218:219], v[244:245], 0, s[44:45]
	s_mov_b32 m0, s66
	s_nop 0
	global_load_lds_dwordx4 v[218:219], off
	v_lshl_add_u64 v[218:219], v[246:247], 0, s[44:45]
	s_mov_b32 m0, s67
	s_nop 0
	global_load_lds_dwordx4 v[218:219], off
	s_waitcnt vmcnt(8)
	s_waitcnt lgkmcnt(0)
	s_setprio 1
	s_barrier
	v_mfma_f32_16x16x32_bf16 v[114:117], v[130:133], v[162:165], v[114:117]
	v_mfma_f32_16x16x32_bf16 v[82:85], v[138:141], v[162:165], v[82:85]
	v_mfma_f32_16x16x32_bf16 v[86:89], v[138:141], v[170:173], v[86:89]
	v_mfma_f32_16x16x32_bf16 v[118:121], v[130:133], v[170:173], v[118:121]
	v_mfma_f32_16x16x32_bf16 v[122:125], v[130:133], v[202:205], v[122:125]
	v_mfma_f32_16x16x32_bf16 v[94:97], v[138:141], v[202:205], v[94:97]
	v_mfma_f32_16x16x32_bf16 v[106:109], v[138:141], v[210:213], v[106:109]
	v_mfma_f32_16x16x32_bf16 v[126:129], v[130:133], v[210:213], v[126:129]
	v_mfma_f32_16x16x32_bf16 v[114:117], v[134:137], v[166:169], v[114:117]
	v_mfma_f32_16x16x32_bf16 v[82:85], v[142:145], v[166:169], v[82:85]
	v_mfma_f32_16x16x32_bf16 v[86:89], v[142:145], v[174:177], v[86:89]
	v_mfma_f32_16x16x32_bf16 v[118:121], v[134:137], v[174:177], v[118:121]
	v_mfma_f32_16x16x32_bf16 v[122:125], v[134:137], v[206:209], v[122:125]
	v_mfma_f32_16x16x32_bf16 v[94:97], v[142:145], v[206:209], v[94:97]
	v_mfma_f32_16x16x32_bf16 v[106:109], v[142:145], v[214:217], v[106:109]
	v_mfma_f32_16x16x32_bf16 v[126:129], v[134:137], v[214:217], v[126:129]
	s_setprio 0
	s_setprio 1
	v_mfma_f32_16x16x32_bf16 v[50:53], v[146:149], v[162:165], v[50:53]
	v_mfma_f32_16x16x32_bf16 v[18:21], v[154:157], v[162:165], v[18:21]
	v_mfma_f32_16x16x32_bf16 v[22:25], v[154:157], v[170:173], v[22:25]
	v_mfma_f32_16x16x32_bf16 v[54:57], v[146:149], v[170:173], v[54:57]
	v_mfma_f32_16x16x32_bf16 v[62:65], v[146:149], v[202:205], v[62:65]
	v_mfma_f32_16x16x32_bf16 v[30:33], v[154:157], v[202:205], v[30:33]
	v_mfma_f32_16x16x32_bf16 v[42:45], v[154:157], v[210:213], v[42:45]
	v_mfma_f32_16x16x32_bf16 v[74:77], v[146:149], v[210:213], v[74:77]
	v_mfma_f32_16x16x32_bf16 v[50:53], v[150:153], v[166:169], v[50:53]
	v_mfma_f32_16x16x32_bf16 v[18:21], v[158:161], v[166:169], v[18:21]
	v_mfma_f32_16x16x32_bf16 v[22:25], v[158:161], v[174:177], v[22:25]
	v_mfma_f32_16x16x32_bf16 v[54:57], v[150:153], v[174:177], v[54:57]
	v_mfma_f32_16x16x32_bf16 v[62:65], v[150:153], v[206:209], v[62:65]
	v_mfma_f32_16x16x32_bf16 v[30:33], v[158:161], v[206:209], v[30:33]
	v_mfma_f32_16x16x32_bf16 v[42:45], v[158:161], v[214:217], v[42:45]
	v_mfma_f32_16x16x32_bf16 v[74:77], v[150:153], v[214:217], v[74:77]
	s_barrier
	s_setprio 0
	s_add_i32 s26, s26, 2
	s_add_u32 s0, s0, 0x100
	s_addc_u32 s1, s1, 0
	s_add_u32 s24, s24, 0x100
	s_addc_u32 s25, s25, 0
	s_cmp_gt_u32 s26, 61
	s_cbranch_scc0 .LBB0_672
	s_and_b64 vcc, exec, s[90:91]
	s_cbranch_vccz .LBB0_675
	s_barrier

.LBB0_788:
	ds_read_b128 v[156:159], v153
	ds_read_b128 v[160:163], v153 offset:1024
	ds_read_b128 v[164:167], v153 offset:2048
	ds_read_b128 v[168:171], v153 offset:3072
	ds_read_b128 v[172:175], v154
	ds_read_b128 v[176:179], v154 offset:1024
	ds_read_b128 v[180:183], v154 offset:2048
	ds_read_b128 v[184:187], v154 offset:3072
	s_add_u32 s36, s26, 0xfff00080
	s_addc_u32 s37, s27, -1
	s_cmp_eq_u32 s54, 60
	s_cselect_b32 s39, s19, s37
	s_cselect_b32 s38, s50, s36
	s_cselect_b32 s37, s17, s53
	s_cselect_b32 s36, s51, s52
	v_lshl_add_u64 v[148:149], s[26:27], 0, v[140:141]
	s_add_i32 m0, s25, 0xc000
	ds_read_b128 v[188:191], v155
	ds_read_b128 v[192:195], v155 offset:1024
	ds_read_b128 v[196:199], v155 offset:2048
	ds_read_b128 v[200:203], v155 offset:3072
	ds_read_b128 v[204:207], v155 offset:4096
	ds_read_b128 v[208:211], v155 offset:5120
	ds_read_b128 v[212:215], v155 offset:6144
	ds_read_b128 v[216:219], v155 offset:7168
	global_load_lds_dwordx4 v[148:149], off
	v_lshl_add_u64 v[148:149], s[26:27], 0, v[142:143]
	s_add_i32 m0, s25, 0xe000
	s_nop 0
	global_load_lds_dwordx4 v[148:149], off
	s_waitcnt vmcnt(8)
	s_waitcnt lgkmcnt(0)
	s_setprio 1
	s_barrier
	v_mfma_f32_16x16x32_bf16 v[126:129], v[156:159], v[188:191], v[126:129]
	v_mfma_f32_16x16x32_bf16 v[122:125], v[164:167], v[188:191], v[122:125]
	v_mfma_f32_16x16x32_bf16 v[114:117], v[164:167], v[196:199], v[114:117]
	v_mfma_f32_16x16x32_bf16 v[118:121], v[156:159], v[196:199], v[118:121]
	v_mfma_f32_16x16x32_bf16 v[94:97], v[156:159], v[204:207], v[94:97]
	v_mfma_f32_16x16x32_bf16 v[90:93], v[164:167], v[204:207], v[90:93]
	v_mfma_f32_16x16x32_bf16 v[82:85], v[164:167], v[212:215], v[82:85]
	v_mfma_f32_16x16x32_bf16 v[86:89], v[156:159], v[212:215], v[86:89]
	v_mfma_f32_16x16x32_bf16 v[126:129], v[160:163], v[192:195], v[126:129]
	v_mfma_f32_16x16x32_bf16 v[122:125], v[168:171], v[192:195], v[122:125]
	v_mfma_f32_16x16x32_bf16 v[114:117], v[168:171], v[200:203], v[114:117]
	v_mfma_f32_16x16x32_bf16 v[118:121], v[160:163], v[200:203], v[118:121]
	v_mfma_f32_16x16x32_bf16 v[94:97], v[160:163], v[208:211], v[94:97]
	v_mfma_f32_16x16x32_bf16 v[90:93], v[168:171], v[208:211], v[90:93]
	v_mfma_f32_16x16x32_bf16 v[82:85], v[168:171], v[216:219], v[82:85]
	v_mfma_f32_16x16x32_bf16 v[86:89], v[160:163], v[216:219], v[86:89]
	s_setprio 0
	s_setprio 1
	v_mfma_f32_16x16x32_bf16 v[110:113], v[172:175], v[188:191], v[110:113]
	v_mfma_f32_16x16x32_bf16 v[106:109], v[180:183], v[188:191], v[106:109]
	v_mfma_f32_16x16x32_bf16 v[98:101], v[180:183], v[196:199], v[98:101]
	v_mfma_f32_16x16x32_bf16 v[102:105], v[172:175], v[196:199], v[102:105]
	v_mfma_f32_16x16x32_bf16 v[78:81], v[172:175], v[204:207], v[78:81]
	v_mfma_f32_16x16x32_bf16 v[74:77], v[180:183], v[204:207], v[74:77]
	v_mfma_f32_16x16x32_bf16 v[66:69], v[180:183], v[212:215], v[66:69]
	v_mfma_f32_16x16x32_bf16 v[70:73], v[172:175], v[212:215], v[70:73]
	v_mfma_f32_16x16x32_bf16 v[110:113], v[176:179], v[192:195], v[110:113]
	v_mfma_f32_16x16x32_bf16 v[106:109], v[184:187], v[192:195], v[106:109]
	v_mfma_f32_16x16x32_bf16 v[98:101], v[184:187], v[200:203], v[98:101]
	v_mfma_f32_16x16x32_bf16 v[102:105], v[176:179], v[200:203], v[102:105]
	v_mfma_f32_16x16x32_bf16 v[78:81], v[176:179], v[208:211], v[78:81]
	v_mfma_f32_16x16x32_bf16 v[74:77], v[184:187], v[208:211], v[74:77]
	v_mfma_f32_16x16x32_bf16 v[66:69], v[184:187], v[216:219], v[66:69]
	v_mfma_f32_16x16x32_bf16 v[70:73], v[176:179], v[216:219], v[70:73]
	s_barrier
	s_setprio 0
	s_add_i32 s55, s44, s13
	v_lshl_add_u64 v[148:149], s[36:37], 0, v[134:135]
	s_mov_b32 m0, s55
	ds_read_b128 v[188:191], v155 offset:16384
	ds_read_b128 v[192:195], v155 offset:17408
	ds_read_b128 v[196:199], v155 offset:18432
	ds_read_b128 v[200:203], v155 offset:19456
	ds_read_b128 v[204:207], v155 offset:20480
	ds_read_b128 v[208:211], v155 offset:21504
	ds_read_b128 v[212:215], v155 offset:22528
	ds_read_b128 v[216:219], v155 offset:23552
	global_load_lds_dwordx4 v[148:149], off
	s_add_i32 m0, s55, 0x2000
	s_add_u32 s56, s36, 0x100000
	v_lshl_add_u64 v[220:221], s[36:37], 0, v[130:131]
	s_addc_u32 s57, s37, 0
	s_add_i32 s55, s45, s13
	global_load_lds_dwordx4 v[220:221], off
	v_lshl_add_u64 v[224:225], s[56:57], 0, v[134:135]
	s_mov_b32 m0, s55
	v_lshl_add_u64 v[226:227], s[38:39], 0, v[132:133]
	global_load_lds_dwordx4 v[224:225], off
	v_lshl_add_u64 v[224:225], s[56:57], 0, v[130:131]
	s_add_i32 m0, s55, 0x2000
	s_nop 0
	global_load_lds_dwordx4 v[224:225], off
	v_lshl_add_u64 v[224:225], s[38:39], 0, v[136:137]
	s_mov_b32 m0, s25
	s_nop 0
	global_load_lds_dwordx4 v[224:225], off
	s_mov_b32 m0, s31
	s_nop 0
	global_load_lds_dwordx4 v[226:227], off
	s_waitcnt vmcnt(8)
	s_waitcnt lgkmcnt(0)
	s_setprio 1
	s_barrier
	v_mfma_f32_16x16x32_bf16 v[62:65], v[156:159], v[188:191], v[62:65]
	v_mfma_f32_16x16x32_bf16 v[58:61], v[164:167], v[188:191], v[58:61]
	v_mfma_f32_16x16x32_bf16 v[50:53], v[164:167], v[196:199], v[50:53]
	v_mfma_f32_16x16x32_bf16 v[54:57], v[156:159], v[196:199], v[54:57]
	v_mfma_f32_16x16x32_bf16 v[30:33], v[156:159], v[204:207], v[30:33]
	v_mfma_f32_16x16x32_bf16 v[26:29], v[164:167], v[204:207], v[26:29]
	v_mfma_f32_16x16x32_bf16 v[18:21], v[164:167], v[212:215], v[18:21]
	v_mfma_f32_16x16x32_bf16 v[22:25], v[156:159], v[212:215], v[22:25]
	v_mfma_f32_16x16x32_bf16 v[62:65], v[160:163], v[192:195], v[62:65]
	v_mfma_f32_16x16x32_bf16 v[58:61], v[168:171], v[192:195], v[58:61]
	v_mfma_f32_16x16x32_bf16 v[50:53], v[168:171], v[200:203], v[50:53]
	v_mfma_f32_16x16x32_bf16 v[54:57], v[160:163], v[200:203], v[54:57]
	v_mfma_f32_16x16x32_bf16 v[30:33], v[160:163], v[208:211], v[30:33]
	v_mfma_f32_16x16x32_bf16 v[26:29], v[168:171], v[208:211], v[26:29]
	v_mfma_f32_16x16x32_bf16 v[18:21], v[168:171], v[216:219], v[18:21]
	v_mfma_f32_16x16x32_bf16 v[22:25], v[160:163], v[216:219], v[22:25]
	s_setprio 0
	s_setprio 1
	v_mfma_f32_16x16x32_bf16 v[46:49], v[172:175], v[188:191], v[46:49]
	v_mfma_f32_16x16x32_bf16 v[42:45], v[180:183], v[188:191], v[42:45]
	v_mfma_f32_16x16x32_bf16 v[34:37], v[180:183], v[196:199], v[34:37]
	v_mfma_f32_16x16x32_bf16 v[38:41], v[172:175], v[196:199], v[38:41]
	v_mfma_f32_16x16x32_bf16 v[14:17], v[172:175], v[204:207], v[14:17]
	v_mfma_f32_16x16x32_bf16 v[10:13], v[180:183], v[204:207], v[10:13]
	v_mfma_f32_16x16x32_bf16 v[2:5], v[180:183], v[212:215], v[2:5]
	v_mfma_f32_16x16x32_bf16 v[6:9], v[172:175], v[212:215], v[6:9]
	v_mfma_f32_16x16x32_bf16 v[46:49], v[176:179], v[192:195], v[46:49]
	v_mfma_f32_16x16x32_bf16 v[42:45], v[184:187], v[192:195], v[42:45]
	v_mfma_f32_16x16x32_bf16 v[34:37], v[184:187], v[200:203], v[34:37]
	v_mfma_f32_16x16x32_bf16 v[38:41], v[176:179], v[200:203], v[38:41]
	v_mfma_f32_16x16x32_bf16 v[14:17], v[176:179], v[208:211], v[14:17]
	v_mfma_f32_16x16x32_bf16 v[10:13], v[184:187], v[208:211], v[10:13]
	v_mfma_f32_16x16x32_bf16 v[2:5], v[184:187], v[216:219], v[2:5]
	v_mfma_f32_16x16x32_bf16 v[6:9], v[176:179], v[216:219], v[6:9]
	s_barrier
	s_setprio 0
	s_add_i32 s55, 0, 0x18000
	s_add_i32 s56, 0, 0x1c000
	v_add_u32_e32 v168, s55, v151
	v_add_u32_e32 v184, s56, v151
	ds_read_b128 v[156:159], v168
	ds_read_b128 v[160:163], v168 offset:1024
	ds_read_b128 v[164:167], v168 offset:2048
	ds_read_b128 v[168:171], v168 offset:3072
	ds_read_b128 v[172:175], v184
	ds_read_b128 v[176:179], v184 offset:1024
	ds_read_b128 v[180:183], v184 offset:2048
	ds_read_b128 v[184:187], v184 offset:3072
	s_add_u32 s38, s38, 0x100000
	s_addc_u32 s39, s39, 0
	s_mov_b32 m0, s34
	v_lshl_add_u64 v[228:229], s[38:39], 0, v[136:137]
	ds_read_b128 v[188:191], v155 offset:32768
	ds_read_b128 v[192:195], v155 offset:33792
	ds_read_b128 v[196:199], v155 offset:34816
	ds_read_b128 v[200:203], v155 offset:35840
	ds_read_b128 v[204:207], v155 offset:36864
	ds_read_b128 v[208:211], v155 offset:37888
	ds_read_b128 v[212:215], v155 offset:38912
	ds_read_b128 v[216:219], v155 offset:39936
	global_load_lds_dwordx4 v[228:229], off
	v_lshl_add_u64 v[228:229], s[38:39], 0, v[132:133]
	s_mov_b32 m0, s35
	s_nop 0
	global_load_lds_dwordx4 v[228:229], off
	s_waitcnt vmcnt(8)
	s_waitcnt lgkmcnt(0)
	s_setprio 1
	s_barrier
	v_mfma_f32_16x16x32_bf16 v[126:129], v[156:159], v[188:191], v[126:129]
	v_mfma_f32_16x16x32_bf16 v[122:125], v[164:167], v[188:191], v[122:125]
	v_mfma_f32_16x16x32_bf16 v[114:117], v[164:167], v[196:199], v[114:117]
	v_mfma_f32_16x16x32_bf16 v[118:121], v[156:159], v[196:199], v[118:121]
	v_mfma_f32_16x16x32_bf16 v[94:97], v[156:159], v[204:207], v[94:97]
	v_mfma_f32_16x16x32_bf16 v[90:93], v[164:167], v[204:207], v[90:93]
	v_mfma_f32_16x16x32_bf16 v[82:85], v[164:167], v[212:215], v[82:85]
	v_mfma_f32_16x16x32_bf16 v[86:89], v[156:159], v[212:215], v[86:89]
	v_mfma_f32_16x16x32_bf16 v[126:129], v[160:163], v[192:195], v[126:129]
	v_mfma_f32_16x16x32_bf16 v[122:125], v[168:171], v[192:195], v[122:125]
	v_mfma_f32_16x16x32_bf16 v[114:117], v[168:171], v[200:203], v[114:117]
	v_mfma_f32_16x16x32_bf16 v[118:121], v[160:163], v[200:203], v[118:121]
	v_mfma_f32_16x16x32_bf16 v[94:97], v[160:163], v[208:211], v[94:97]
	v_mfma_f32_16x16x32_bf16 v[90:93], v[168:171], v[208:211], v[90:93]
	v_mfma_f32_16x16x32_bf16 v[82:85], v[168:171], v[216:219], v[82:85]
	v_mfma_f32_16x16x32_bf16 v[86:89], v[160:163], v[216:219], v[86:89]
	s_setprio 0
	s_setprio 1
	v_mfma_f32_16x16x32_bf16 v[110:113], v[172:175], v[188:191], v[110:113]
	v_mfma_f32_16x16x32_bf16 v[106:109], v[180:183], v[188:191], v[106:109]
	v_mfma_f32_16x16x32_bf16 v[98:101], v[180:183], v[196:199], v[98:101]
	v_mfma_f32_16x16x32_bf16 v[102:105], v[172:175], v[196:199], v[102:105]
	v_mfma_f32_16x16x32_bf16 v[78:81], v[172:175], v[204:207], v[78:81]
	v_mfma_f32_16x16x32_bf16 v[74:77], v[180:183], v[204:207], v[74:77]
	v_mfma_f32_16x16x32_bf16 v[66:69], v[180:183], v[212:215], v[66:69]
	v_mfma_f32_16x16x32_bf16 v[70:73], v[172:175], v[212:215], v[70:73]
	v_mfma_f32_16x16x32_bf16 v[110:113], v[176:179], v[192:195], v[110:113]
	v_mfma_f32_16x16x32_bf16 v[106:109], v[184:187], v[192:195], v[106:109]
	v_mfma_f32_16x16x32_bf16 v[98:101], v[184:187], v[200:203], v[98:101]
	v_mfma_f32_16x16x32_bf16 v[102:105], v[176:179], v[200:203], v[102:105]
	v_mfma_f32_16x16x32_bf16 v[78:81], v[176:179], v[208:211], v[78:81]
	v_mfma_f32_16x16x32_bf16 v[74:77], v[184:187], v[208:211], v[74:77]
	v_mfma_f32_16x16x32_bf16 v[66:69], v[184:187], v[216:219], v[66:69]
	v_mfma_f32_16x16x32_bf16 v[70:73], v[176:179], v[216:219], v[70:73]
	s_barrier
	s_setprio 0
	s_add_i32 s38, s55, s13
	v_lshl_add_u64 v[148:149], v[148:149], 0, s[6:7]
	s_mov_b32 m0, s38
	ds_read_b128 v[188:191], v155 offset:49152
	ds_read_b128 v[192:195], v155 offset:50176
	ds_read_b128 v[196:199], v155 offset:51200
	ds_read_b128 v[200:203], v155 offset:52224
	ds_read_b128 v[204:207], v155 offset:53248
	ds_read_b128 v[208:211], v155 offset:54272
	ds_read_b128 v[212:215], v155 offset:55296
	ds_read_b128 v[216:219], v155 offset:56320
	global_load_lds_dwordx4 v[148:149], off
	s_add_i32 m0, s38, 0x2000
	s_add_u32 s36, s36, 0x100080
	v_lshl_add_u64 v[148:149], v[220:221], 0, s[6:7]
	s_addc_u32 s37, s37, 0
	s_add_i32 s38, s56, s13
	global_load_lds_dwordx4 v[148:149], off
	v_lshl_add_u64 v[148:149], s[36:37], 0, v[134:135]
	s_mov_b32 m0, s38
	s_nop 0
	global_load_lds_dwordx4 v[148:149], off
	v_lshl_add_u64 v[148:149], s[36:37], 0, v[130:131]
	s_add_i32 m0, s38, 0x2000
	s_nop 0
	global_load_lds_dwordx4 v[148:149], off
	v_lshl_add_u64 v[148:149], v[224:225], 0, s[6:7]
	s_mov_b32 m0, s41
	s_nop 0
	global_load_lds_dwordx4 v[148:149], off
	v_lshl_add_u64 v[148:149], v[226:227], 0, s[6:7]
	s_mov_b32 m0, s42
	s_nop 0
	global_load_lds_dwordx4 v[148:149], off
	s_waitcnt vmcnt(8)
	s_waitcnt lgkmcnt(0)
	s_setprio 1
	s_barrier
	v_mfma_f32_16x16x32_bf16 v[62:65], v[156:159], v[188:191], v[62:65]
	v_mfma_f32_16x16x32_bf16 v[58:61], v[164:167], v[188:191], v[58:61]
	v_mfma_f32_16x16x32_bf16 v[50:53], v[164:167], v[196:199], v[50:53]
	v_mfma_f32_16x16x32_bf16 v[54:57], v[156:159], v[196:199], v[54:57]
	v_mfma_f32_16x16x32_bf16 v[30:33], v[156:159], v[204:207], v[30:33]
	v_mfma_f32_16x16x32_bf16 v[26:29], v[164:167], v[204:207], v[26:29]
	v_mfma_f32_16x16x32_bf16 v[18:21], v[164:167], v[212:215], v[18:21]
	v_mfma_f32_16x16x32_bf16 v[22:25], v[156:159], v[212:215], v[22:25]
	v_mfma_f32_16x16x32_bf16 v[62:65], v[160:163], v[192:195], v[62:65]
	v_mfma_f32_16x16x32_bf16 v[58:61], v[168:171], v[192:195], v[58:61]
	v_mfma_f32_16x16x32_bf16 v[50:53], v[168:171], v[200:203], v[50:53]
	v_mfma_f32_16x16x32_bf16 v[54:57], v[160:163], v[200:203], v[54:57]
	v_mfma_f32_16x16x32_bf16 v[30:33], v[160:163], v[208:211], v[30:33]
	v_mfma_f32_16x16x32_bf16 v[26:29], v[168:171], v[208:211], v[26:29]
	v_mfma_f32_16x16x32_bf16 v[18:21], v[168:171], v[216:219], v[18:21]
	v_mfma_f32_16x16x32_bf16 v[22:25], v[160:163], v[216:219], v[22:25]
	s_setprio 0
	s_setprio 1
	v_mfma_f32_16x16x32_bf16 v[46:49], v[172:175], v[188:191], v[46:49]
	v_mfma_f32_16x16x32_bf16 v[42:45], v[180:183], v[188:191], v[42:45]
	v_mfma_f32_16x16x32_bf16 v[34:37], v[180:183], v[196:199], v[34:37]
	v_mfma_f32_16x16x32_bf16 v[38:41], v[172:175], v[196:199], v[38:41]
	v_mfma_f32_16x16x32_bf16 v[14:17], v[172:175], v[204:207], v[14:17]
	v_mfma_f32_16x16x32_bf16 v[10:13], v[180:183], v[204:207], v[10:13]
	v_mfma_f32_16x16x32_bf16 v[2:5], v[180:183], v[212:215], v[2:5]
	v_mfma_f32_16x16x32_bf16 v[6:9], v[172:175], v[212:215], v[6:9]
	v_mfma_f32_16x16x32_bf16 v[46:49], v[176:179], v[192:195], v[46:49]
	v_mfma_f32_16x16x32_bf16 v[42:45], v[184:187], v[192:195], v[42:45]
	v_mfma_f32_16x16x32_bf16 v[34:37], v[184:187], v[200:203], v[34:37]
	v_mfma_f32_16x16x32_bf16 v[38:41], v[176:179], v[200:203], v[38:41]
	v_mfma_f32_16x16x32_bf16 v[14:17], v[176:179], v[208:211], v[14:17]
	v_mfma_f32_16x16x32_bf16 v[10:13], v[184:187], v[208:211], v[10:13]
	v_mfma_f32_16x16x32_bf16 v[2:5], v[184:187], v[216:219], v[2:5]
	v_mfma_f32_16x16x32_bf16 v[6:9], v[176:179], v[216:219], v[6:9]
	s_barrier
	s_setprio 0
	s_add_i32 s54, s54, 2
	s_add_u32 s26, s26, 0x100
	s_addc_u32 s27, s27, 0
	s_add_u32 s52, s52, 0x100
	s_addc_u32 s53, s53, 0
	s_cmp_gt_u32 s54, 61
	s_cbranch_scc0 .LBB0_788
	s_and_b64 vcc, exec, s[8:9]
	s_cbranch_vccz .LBB0_791
	s_barrier

.LBB0_912:
	s_add_u32 s6, s74, 0x13000000
	s_addc_u32 s7, s75, 0
	s_add_u32 s8, s74, 0x6400000
	s_addc_u32 s9, s75, 0
	v_and_b32_e32 v66, 0x7c, v150
	s_add_u32 s10, s74, 0x400000
	v_mul_u32_u24_e32 v1, 0x210, v1
	v_lshlrev_b32_e32 v67, 2, v66
	s_addc_u32 s11, s75, 0
	s_lshl_b32 s3, s79, 2
	v_add3_u32 v1, 0, v1, v67
	v_lshrrev_b32_e32 v67, 4, v0
	s_add_i32 s3, s3, 0
	s_movk_i32 s2, 0x210
	s_mov_b32 s5, 0
	v_and_b32_e32 v67, 30, v67
	v_mov_b32_e32 v68, s3
	v_mov_b32_e32 v69, 0
	v_mad_u32_u24 v102, v222, s2, v68
	v_or_b32_e32 v103, 0x80, v67
	s_mov_b64 s[20:21], 0
	s_movk_i32 s15, 0xe000
	s_mov_b32 s30, s78
	s_mov_b32 s24, s5
	s_mov_b32 s35, 0
	s_mov_b32 s31, 0
	s_mov_b32 s4, s5
	s_mov_b32 s34, s5
	s_mov_b64 s[18:19], 0
	s_mov_b32 s98, 0
	s_branch .LBB0_914
.Lcvc_steady:
	s_waitcnt vmcnt(46)
	v_cvt_pk_bf16_f32 v70, v6, v2
	v_cvt_pk_bf16_f32 v71, v7, v3
	v_cvt_pk_bf16_f32 v72, v8, v4
	v_cvt_pk_bf16_f32 v73, v9, v5
	ds_write_b128 v1, v[70:73]
	s_waitcnt vmcnt(44)
	v_cvt_pk_bf16_f32 v70, v14, v10
	v_cvt_pk_bf16_f32 v71, v15, v11
	v_cvt_pk_bf16_f32 v72, v16, v12
	v_cvt_pk_bf16_f32 v73, v17, v13
	v_cndmask_b32_e64 v68, 0, 1, s[38:39]
	ds_write_b128 v1, v[70:73] offset:8448
	s_waitcnt vmcnt(42)
	v_cvt_pk_bf16_f32 v70, v22, v18
	v_cvt_pk_bf16_f32 v71, v23, v19
	v_cvt_pk_bf16_f32 v72, v24, v20
	v_cvt_pk_bf16_f32 v73, v25, v21
	v_cmp_ne_u32_e64 s[2:3], 1, v68
	s_andn2_b64 vcc, exec, s[38:39]
	ds_write_b128 v1, v[70:73] offset:16896
	s_waitcnt vmcnt(40)
	v_cvt_pk_bf16_f32 v70, v30, v26
	v_cvt_pk_bf16_f32 v71, v31, v27
	v_cvt_pk_bf16_f32 v72, v32, v28
	v_cvt_pk_bf16_f32 v73, v33, v29
	ds_write_b128 v1, v[70:73] offset:25344
	s_cbranch_vccnz .Lcvc_snomore
	v_or_b32_e32 v2, s35, v67
	s_ashr_i32 s25, s35, 31
	s_mul_i32 s25, s25, s4
	v_mad_u64_u32 v[2:3], s[38:39], v2, s4, 0
	v_add_u32_e32 v3, s25, v3
	v_lshl_add_u64 v[2:3], v[2:3], 2, s[18:19]
	s_ashr_i32 s25, s24, 31
	v_lshl_add_u64 v[2:3], s[24:25], 2, v[2:3]
	v_lshlrev_b32_e32 v68, 2, v66
	v_lshl_add_u64 v[26:27], v[2:3], 0, v[68:69]
	s_lshl_b32 s38, s4, 5
	s_mov_b32 s39, s5
	v_lshl_add_u64 v[10:11], s[38:39], 2, v[26:27]
	s_mul_i32 s38, s4, 33
	v_lshl_add_u64 v[12:13], s[38:39], 2, v[26:27]
	s_lshl_b32 s38, s4, 6
	v_lshl_add_u64 v[18:19], s[38:39], 2, v[26:27]
	s_mul_i32 s38, s4, 0x41
	v_lshl_add_u64 v[20:21], s[38:39], 2, v[26:27]
	s_mul_i32 s38, s4, 0x60
	v_lshl_add_u64 v[2:3], s[4:5], 2, v[26:27]
	v_lshl_add_u64 v[28:29], s[38:39], 2, v[26:27]
	s_mul_i32 s38, s4, 0x61
	global_load_dwordx4 v[6:9], v[26:27], off nt
	s_nop 0
	global_load_dwordx4 v[2:5], v[2:3], off nt
	v_lshl_add_u64 v[26:27], s[38:39], 2, v[26:27]
	global_load_dwordx4 v[14:17], v[10:11], off nt
	s_nop 0
	global_load_dwordx4 v[10:13], v[12:13], off nt
	s_nop 0
	global_load_dwordx4 v[22:25], v[18:19], off nt
	s_nop 0
	global_load_dwordx4 v[18:21], v[20:21], off nt
	s_nop 0
	global_load_dwordx4 v[30:33], v[28:29], off nt
	s_nop 0
	global_load_dwordx4 v[26:29], v[26:27], off nt
.Lcvc_smid:
	s_waitcnt vmcnt(46)
	v_cvt_pk_bf16_f32 v70, v34, v38
	v_cvt_pk_bf16_f32 v71, v35, v39
	v_cvt_pk_bf16_f32 v72, v36, v40
	v_cvt_pk_bf16_f32 v73, v37, v41
	ds_write_b128 v1, v[70:73] offset:33792
	s_waitcnt vmcnt(44)
	v_cvt_pk_bf16_f32 v70, v42, v46
	v_cvt_pk_bf16_f32 v71, v43, v47
	v_cvt_pk_bf16_f32 v72, v44, v48
	v_cvt_pk_bf16_f32 v73, v45, v49
	ds_write_b128 v1, v[70:73] offset:42240
	s_waitcnt vmcnt(42)
	v_cvt_pk_bf16_f32 v70, v50, v54
	v_cvt_pk_bf16_f32 v71, v51, v55
	v_cvt_pk_bf16_f32 v72, v52, v56
	v_cvt_pk_bf16_f32 v73, v53, v57
	s_and_b64 vcc, exec, s[2:3]
	ds_write_b128 v1, v[70:73] offset:50688
	s_waitcnt vmcnt(40)
	v_cvt_pk_bf16_f32 v70, v58, v62
	v_cvt_pk_bf16_f32 v71, v59, v63
	v_cvt_pk_bf16_f32 v72, v60, v64
	v_cvt_pk_bf16_f32 v73, v61, v65
	ds_write_b128 v1, v[70:73] offset:59136
	s_cbranch_vccnz .LBB0_932
	v_or_b32_e32 v34, s35, v103
	s_ashr_i32 s2, s35, 31
	s_mul_i32 s25, s2, s4
	v_mad_u64_u32 v[34:35], s[2:3], v34, s4, 0
	v_add_u32_e32 v35, s25, v35
	v_lshl_add_u64 v[34:35], v[34:35], 2, s[18:19]
	s_ashr_i32 s25, s24, 31
	v_lshl_add_u64 v[34:35], s[24:25], 2, v[34:35]
	v_lshlrev_b32_e32 v68, 2, v66
	v_lshl_add_u64 v[58:59], v[34:35], 0, v[68:69]
	s_lshl_b32 s2, s4, 5
	s_mov_b32 s3, s5
	v_lshl_add_u64 v[42:43], s[2:3], 2, v[58:59]
	s_mul_i32 s2, s4, 33
	v_lshl_add_u64 v[46:47], s[2:3], 2, v[58:59]
	s_lshl_b32 s2, s4, 6
	v_lshl_add_u64 v[50:51], s[2:3], 2, v[58:59]
	s_mul_i32 s2, s4, 0x41
	v_lshl_add_u64 v[54:55], s[2:3], 2, v[58:59]
	s_mul_i32 s2, s4, 0x60
	v_lshl_add_u64 v[60:61], s[2:3], 2, v[58:59]
	s_mul_i32 s2, s4, 0x61
	v_lshl_add_u64 v[38:39], s[4:5], 2, v[58:59]
	v_lshl_add_u64 v[62:63], s[2:3], 2, v[58:59]
	global_load_dwordx4 v[34:37], v[58:59], off nt
	s_nop 0
	global_load_dwordx4 v[38:41], v[38:39], off nt
	s_nop 0
	global_load_dwordx4 v[42:45], v[42:43], off nt
	s_nop 0
	global_load_dwordx4 v[46:49], v[46:47], off nt
	s_nop 0
	global_load_dwordx4 v[50:53], v[50:51], off nt
	s_nop 0
	global_load_dwordx4 v[54:57], v[54:55], off nt
	s_nop 0
	global_load_dwordx4 v[58:61], v[60:61], off nt
	s_nop 0
	global_load_dwordx4 v[62:65], v[62:63], off nt
	s_branch .LBB0_932

.LBB0_928:
	s_cmp_lg_u32 s98, 0
	s_cbranch_scc1 .Lcvc_steady
	s_waitcnt vmcnt(14)
	v_cvt_pk_bf16_f32 v70, v6, v2
	v_cvt_pk_bf16_f32 v71, v7, v3
	v_cvt_pk_bf16_f32 v72, v8, v4
	v_cvt_pk_bf16_f32 v73, v9, v5
	ds_write_b128 v1, v[70:73]
	s_waitcnt vmcnt(12)
	v_cvt_pk_bf16_f32 v70, v14, v10
	v_cvt_pk_bf16_f32 v71, v15, v11
	v_cvt_pk_bf16_f32 v72, v16, v12
	v_cvt_pk_bf16_f32 v73, v17, v13
	v_cndmask_b32_e64 v68, 0, 1, s[38:39]
	ds_write_b128 v1, v[70:73] offset:8448
	s_waitcnt vmcnt(10)
	v_cvt_pk_bf16_f32 v70, v22, v18
	v_cvt_pk_bf16_f32 v71, v23, v19
	v_cvt_pk_bf16_f32 v72, v24, v20
	v_cvt_pk_bf16_f32 v73, v25, v21
	v_cmp_ne_u32_e64 s[2:3], 1, v68
	s_andn2_b64 vcc, exec, s[38:39]
	ds_write_b128 v1, v[70:73] offset:16896
	s_waitcnt vmcnt(8)
	v_cvt_pk_bf16_f32 v70, v30, v26
	v_cvt_pk_bf16_f32 v71, v31, v27
	v_cvt_pk_bf16_f32 v72, v32, v28
	v_cvt_pk_bf16_f32 v73, v33, v29
	ds_write_b128 v1, v[70:73] offset:25344
	s_cbranch_vccnz .Lcvc_fnomore
	v_or_b32_e32 v2, s35, v67
	s_ashr_i32 s25, s35, 31
	s_mul_i32 s25, s25, s4
	v_mad_u64_u32 v[2:3], s[38:39], v2, s4, 0
	v_add_u32_e32 v3, s25, v3
	v_lshl_add_u64 v[2:3], v[2:3], 2, s[18:19]
	s_ashr_i32 s25, s24, 31
	v_lshl_add_u64 v[2:3], s[24:25], 2, v[2:3]
	v_lshlrev_b32_e32 v68, 2, v66
	v_lshl_add_u64 v[26:27], v[2:3], 0, v[68:69]
	s_lshl_b32 s38, s4, 5
	s_mov_b32 s39, s5
	v_lshl_add_u64 v[10:11], s[38:39], 2, v[26:27]
	s_mul_i32 s38, s4, 33
	v_lshl_add_u64 v[12:13], s[38:39], 2, v[26:27]
	s_lshl_b32 s38, s4, 6
	v_lshl_add_u64 v[18:19], s[38:39], 2, v[26:27]
	s_mul_i32 s38, s4, 0x41
	v_lshl_add_u64 v[20:21], s[38:39], 2, v[26:27]
	s_mul_i32 s38, s4, 0x60
	v_lshl_add_u64 v[2:3], s[4:5], 2, v[26:27]
	v_lshl_add_u64 v[28:29], s[38:39], 2, v[26:27]
	s_mul_i32 s38, s4, 0x61
	global_load_dwordx4 v[6:9], v[26:27], off nt
	s_nop 0
	global_load_dwordx4 v[2:5], v[2:3], off nt
	v_lshl_add_u64 v[26:27], s[38:39], 2, v[26:27]
	global_load_dwordx4 v[14:17], v[10:11], off nt
	s_nop 0
	global_load_dwordx4 v[10:13], v[12:13], off nt
	s_nop 0
	global_load_dwordx4 v[22:25], v[18:19], off nt
	s_nop 0
	global_load_dwordx4 v[18:21], v[20:21], off nt
	s_nop 0
	global_load_dwordx4 v[30:33], v[28:29], off nt
	s_nop 0
	global_load_dwordx4 v[26:29], v[26:27], off nt
.LBB0_930:
	s_waitcnt vmcnt(14)
	v_cvt_pk_bf16_f32 v70, v34, v38
	v_cvt_pk_bf16_f32 v71, v35, v39
	v_cvt_pk_bf16_f32 v72, v36, v40
	v_cvt_pk_bf16_f32 v73, v37, v41
	ds_write_b128 v1, v[70:73] offset:33792
	s_waitcnt vmcnt(12)
	v_cvt_pk_bf16_f32 v70, v42, v46
	v_cvt_pk_bf16_f32 v71, v43, v47
	v_cvt_pk_bf16_f32 v72, v44, v48
	v_cvt_pk_bf16_f32 v73, v45, v49
	ds_write_b128 v1, v[70:73] offset:42240
	s_waitcnt vmcnt(10)
	v_cvt_pk_bf16_f32 v70, v50, v54
	v_cvt_pk_bf16_f32 v71, v51, v55
	v_cvt_pk_bf16_f32 v72, v52, v56
	v_cvt_pk_bf16_f32 v73, v53, v57
	s_and_b64 vcc, exec, s[2:3]
	ds_write_b128 v1, v[70:73] offset:50688
	s_waitcnt vmcnt(8)
	v_cvt_pk_bf16_f32 v70, v58, v62
	v_cvt_pk_bf16_f32 v71, v59, v63
	v_cvt_pk_bf16_f32 v72, v60, v64
	v_cvt_pk_bf16_f32 v73, v61, v65
	ds_write_b128 v1, v[70:73] offset:59136
	s_cbranch_vccnz .LBB0_932
	v_or_b32_e32 v34, s35, v103
	s_ashr_i32 s2, s35, 31
	s_mul_i32 s25, s2, s4
	v_mad_u64_u32 v[34:35], s[2:3], v34, s4, 0
	v_add_u32_e32 v35, s25, v35
	v_lshl_add_u64 v[34:35], v[34:35], 2, s[18:19]
	s_ashr_i32 s25, s24, 31
	v_lshl_add_u64 v[34:35], s[24:25], 2, v[34:35]
	v_lshlrev_b32_e32 v68, 2, v66
	v_lshl_add_u64 v[58:59], v[34:35], 0, v[68:69]
	s_lshl_b32 s2, s4, 5
	s_mov_b32 s3, s5
	v_lshl_add_u64 v[42:43], s[2:3], 2, v[58:59]
	s_mul_i32 s2, s4, 33
	v_lshl_add_u64 v[46:47], s[2:3], 2, v[58:59]
	s_lshl_b32 s2, s4, 6
	v_lshl_add_u64 v[50:51], s[2:3], 2, v[58:59]
	s_mul_i32 s2, s4, 0x41
	v_lshl_add_u64 v[54:55], s[2:3], 2, v[58:59]
	s_mul_i32 s2, s4, 0x60
	v_lshl_add_u64 v[60:61], s[2:3], 2, v[58:59]
	s_mul_i32 s2, s4, 0x61
	v_lshl_add_u64 v[38:39], s[4:5], 2, v[58:59]
	v_lshl_add_u64 v[62:63], s[2:3], 2, v[58:59]
	global_load_dwordx4 v[34:37], v[58:59], off nt
	s_nop 0
	global_load_dwordx4 v[38:41], v[38:39], off nt
	s_nop 0
	global_load_dwordx4 v[42:45], v[42:43], off nt
	s_nop 0
	global_load_dwordx4 v[46:49], v[46:47], off nt
	s_nop 0
	global_load_dwordx4 v[50:53], v[50:51], off nt
	s_nop 0
	global_load_dwordx4 v[54:57], v[54:55], off nt
	s_nop 0
	global_load_dwordx4 v[58:61], v[60:61], off nt
	s_nop 0
	global_load_dwordx4 v[62:65], v[62:63], off nt
.LBB0_932:
	s_mov_b32 s98, 1
	s_waitcnt lgkmcnt(0)
	s_barrier
	s_cmp_lt_i32 s27, 1
	s_cbranch_scc1 .LBB0_937
	s_cmp_eq_u32 s27, 1
	s_mov_b64 s[40:41], -1
	s_cbranch_scc0 .LBB0_939
	s_cmpk_lt_i32 s36, 0x1000
	s_mov_b64 s[40:41], 0
	s_cbranch_scc1 .LBB0_938
	s_cmpk_lt_u32 s36, 0x2000
	s_cbranch_scc1 .LBB0_975
	s_cmpk_lt_u32 s36, 0x2800
	s_cselect_b32 s45, 0, 4
	s_cselect_b32 s25, s15, 0xffffd800
	s_movk_i32 s44, 0x2000
	s_mov_b64 s[2:3], 0
	s_mov_b64 s[38:39], 0
	s_branch .LBB0_941

.LBB0_1040:
	ds_read_b128 v[130:133], v207
	ds_read_b128 v[134:137], v207 offset:1024
	ds_read_b128 v[138:141], v207 offset:2048
	ds_read_b128 v[142:145], v207 offset:3072
	ds_read_b128 v[146:149], v208
	ds_read_b128 v[172:175], v208 offset:1024
	ds_read_b128 v[176:179], v208 offset:2048
	ds_read_b128 v[210:213], v208 offset:3072
	s_add_u32 s10, s8, 0xffd50080
	s_addc_u32 s11, s9, -1
	s_cmpk_eq_i32 s16, 0xa8
	s_cselect_b32 s13, s25, s11
	s_cselect_b32 s12, s24, s10
	s_cselect_b32 s11, s41, s15
	s_cselect_b32 s10, s40, s14
	v_lshl_add_u64 v[180:181], s[8:9], 0, v[166:167]
	s_add_i32 m0, s48, 0xc000
	ds_read_b128 v[214:217], v202
	ds_read_b128 v[218:221], v202 offset:1024
	ds_read_b128 v[224:227], v202 offset:2048
	ds_read_b128 v[228:231], v202 offset:3072
	ds_read_b128 v[232:235], v202 offset:4096
	ds_read_b128 v[236:239], v202 offset:5120
	ds_read_b128 v[240:243], v202 offset:6144
	ds_read_b128 v[244:247], v202 offset:7168
	global_load_lds_dwordx4 v[180:181], off
	v_lshl_add_u64 v[180:181], s[8:9], 0, v[168:169]
	s_add_i32 m0, s48, 0xe000
	s_nop 0
	global_load_lds_dwordx4 v[180:181], off
	s_waitcnt vmcnt(8)
	s_waitcnt lgkmcnt(0)
	s_setprio 1
	s_barrier
	v_mfma_f32_16x16x32_bf16 v[90:93], v[130:133], v[214:217], v[90:93]
	v_mfma_f32_16x16x32_bf16 v[74:77], v[138:141], v[214:217], v[74:77]
	v_mfma_f32_16x16x32_bf16 v[42:45], v[138:141], v[224:227], v[42:45]
	v_mfma_f32_16x16x32_bf16 v[46:49], v[130:133], v[224:227], v[46:49]
	v_mfma_f32_16x16x32_bf16 v[126:129], v[130:133], v[232:235], v[126:129]
	v_mfma_f32_16x16x32_bf16 v[122:125], v[138:141], v[232:235], v[122:125]
	v_mfma_f32_16x16x32_bf16 v[106:109], v[138:141], v[240:243], v[106:109]
	v_mfma_f32_16x16x32_bf16 v[110:113], v[130:133], v[240:243], v[110:113]
	v_mfma_f32_16x16x32_bf16 v[90:93], v[134:137], v[218:221], v[90:93]
	v_mfma_f32_16x16x32_bf16 v[74:77], v[142:145], v[218:221], v[74:77]
	v_mfma_f32_16x16x32_bf16 v[42:45], v[142:145], v[228:231], v[42:45]
	v_mfma_f32_16x16x32_bf16 v[46:49], v[134:137], v[228:231], v[46:49]
	v_mfma_f32_16x16x32_bf16 v[126:129], v[134:137], v[236:239], v[126:129]
	v_mfma_f32_16x16x32_bf16 v[122:125], v[142:145], v[236:239], v[122:125]
	v_mfma_f32_16x16x32_bf16 v[106:109], v[142:145], v[244:247], v[106:109]
	v_mfma_f32_16x16x32_bf16 v[110:113], v[134:137], v[244:247], v[110:113]
	s_setprio 0
	s_setprio 1
	v_mfma_f32_16x16x32_bf16 v[70:73], v[146:149], v[214:217], v[70:73]
	v_mfma_f32_16x16x32_bf16 v[66:69], v[176:179], v[214:217], v[66:69]
	v_mfma_f32_16x16x32_bf16 v[38:41], v[176:179], v[224:227], v[38:41]
	v_mfma_f32_16x16x32_bf16 v[34:37], v[146:149], v[224:227], v[34:37]
	v_mfma_f32_16x16x32_bf16 v[118:121], v[146:149], v[232:235], v[118:121]
	v_mfma_f32_16x16x32_bf16 v[114:117], v[176:179], v[232:235], v[114:117]
	v_mfma_f32_16x16x32_bf16 v[98:101], v[176:179], v[240:243], v[98:101]
	v_mfma_f32_16x16x32_bf16 v[102:105], v[146:149], v[240:243], v[102:105]
	v_mfma_f32_16x16x32_bf16 v[70:73], v[172:175], v[218:221], v[70:73]
	v_mfma_f32_16x16x32_bf16 v[66:69], v[210:213], v[218:221], v[66:69]
	v_mfma_f32_16x16x32_bf16 v[38:41], v[210:213], v[228:231], v[38:41]
	v_mfma_f32_16x16x32_bf16 v[34:37], v[172:175], v[228:231], v[34:37]
	v_mfma_f32_16x16x32_bf16 v[118:121], v[172:175], v[236:239], v[118:121]
	v_mfma_f32_16x16x32_bf16 v[114:117], v[210:213], v[236:239], v[114:117]
	v_mfma_f32_16x16x32_bf16 v[98:101], v[210:213], v[244:247], v[98:101]
	v_mfma_f32_16x16x32_bf16 v[102:105], v[172:175], v[244:247], v[102:105]
	s_barrier
	s_setprio 0
	s_add_i32 s17, s57, s46
	v_lshl_add_u64 v[180:181], s[10:11], 0, v[150:151]
	s_mov_b32 m0, s17
	ds_read_b128 v[214:217], v202 offset:16384
	ds_read_b128 v[218:221], v202 offset:17408
	ds_read_b128 v[224:227], v202 offset:18432
	ds_read_b128 v[228:231], v202 offset:19456
	ds_read_b128 v[232:235], v202 offset:20480
	ds_read_b128 v[236:239], v202 offset:21504
	ds_read_b128 v[240:243], v202 offset:22528
	ds_read_b128 v[244:247], v202 offset:23552
	global_load_lds_dwordx4 v[180:181], off
	s_add_i32 m0, s17, 0x2000
	s_add_u32 s18, s10, 0x2b0000
	v_lshl_add_u64 v[248:249], s[10:11], 0, v[152:153]
	s_addc_u32 s19, s11, 0
	s_add_i32 s17, s58, s46
	global_load_lds_dwordx4 v[248:249], off
	v_lshl_add_u64 v[250:251], s[18:19], 0, v[150:151]
	s_mov_b32 m0, s17
	v_lshl_add_u64 v[252:253], s[12:13], 0, v[152:153]
	global_load_lds_dwordx4 v[250:251], off
	v_lshl_add_u64 v[250:251], s[18:19], 0, v[152:153]
	s_add_i32 m0, s17, 0x2000
	s_nop 0
	global_load_lds_dwordx4 v[250:251], off
	v_lshl_add_u64 v[250:251], s[12:13], 0, v[150:151]
	s_mov_b32 m0, s48
	s_nop 0
	global_load_lds_dwordx4 v[250:251], off
	s_mov_b32 m0, s49
	s_nop 0
	global_load_lds_dwordx4 v[252:253], off
	s_waitcnt vmcnt(8)
	s_waitcnt lgkmcnt(0)
	s_setprio 1
	s_barrier
	v_mfma_f32_16x16x32_bf16 v[94:97], v[130:133], v[214:217], v[94:97]
	v_mfma_f32_16x16x32_bf16 v[86:89], v[138:141], v[214:217], v[86:89]
	v_mfma_f32_16x16x32_bf16 v[78:81], v[138:141], v[224:227], v[78:81]
	v_mfma_f32_16x16x32_bf16 v[82:85], v[130:133], v[224:227], v[82:85]
	v_mfma_f32_16x16x32_bf16 v[30:33], v[130:133], v[232:235], v[30:33]
	v_mfma_f32_16x16x32_bf16 v[26:29], v[138:141], v[232:235], v[26:29]
	v_mfma_f32_16x16x32_bf16 v[18:21], v[138:141], v[240:243], v[18:21]
	v_mfma_f32_16x16x32_bf16 v[22:25], v[130:133], v[240:243], v[22:25]
	v_mfma_f32_16x16x32_bf16 v[94:97], v[134:137], v[218:221], v[94:97]
	v_mfma_f32_16x16x32_bf16 v[86:89], v[142:145], v[218:221], v[86:89]
	v_mfma_f32_16x16x32_bf16 v[78:81], v[142:145], v[228:231], v[78:81]
	v_mfma_f32_16x16x32_bf16 v[82:85], v[134:137], v[228:231], v[82:85]
	v_mfma_f32_16x16x32_bf16 v[30:33], v[134:137], v[236:239], v[30:33]
	v_mfma_f32_16x16x32_bf16 v[26:29], v[142:145], v[236:239], v[26:29]
	v_mfma_f32_16x16x32_bf16 v[18:21], v[142:145], v[244:247], v[18:21]
	v_mfma_f32_16x16x32_bf16 v[22:25], v[134:137], v[244:247], v[22:25]
	s_setprio 0
	s_setprio 1
	v_mfma_f32_16x16x32_bf16 v[62:65], v[146:149], v[214:217], v[62:65]
	v_mfma_f32_16x16x32_bf16 v[58:61], v[176:179], v[214:217], v[58:61]
	v_mfma_f32_16x16x32_bf16 v[50:53], v[176:179], v[224:227], v[50:53]
	v_mfma_f32_16x16x32_bf16 v[54:57], v[146:149], v[224:227], v[54:57]
	v_mfma_f32_16x16x32_bf16 v[14:17], v[146:149], v[232:235], v[14:17]
	v_mfma_f32_16x16x32_bf16 v[6:9], v[176:179], v[232:235], v[6:9]
	v_mfma_f32_16x16x32_bf16 v[2:5], v[176:179], v[240:243], v[2:5]
	v_mfma_f32_16x16x32_bf16 v[10:13], v[146:149], v[240:243], v[10:13]
	v_mfma_f32_16x16x32_bf16 v[62:65], v[172:175], v[218:221], v[62:65]
	v_mfma_f32_16x16x32_bf16 v[58:61], v[210:213], v[218:221], v[58:61]
	v_mfma_f32_16x16x32_bf16 v[50:53], v[210:213], v[228:231], v[50:53]
	v_mfma_f32_16x16x32_bf16 v[54:57], v[172:175], v[228:231], v[54:57]
	v_mfma_f32_16x16x32_bf16 v[14:17], v[172:175], v[236:239], v[14:17]
	v_mfma_f32_16x16x32_bf16 v[6:9], v[210:213], v[236:239], v[6:9]
	v_mfma_f32_16x16x32_bf16 v[2:5], v[210:213], v[244:247], v[2:5]
	v_mfma_f32_16x16x32_bf16 v[10:13], v[172:175], v[244:247], v[10:13]
	s_barrier
	s_setprio 0
	s_add_i32 s17, 0, 0x18000
	s_add_i32 s18, 0, 0x1c000
	v_add_u32_e32 v142, s17, v182
	v_add_u32_e32 v154, s18, v182
	ds_read_b128 v[130:133], v142
	ds_read_b128 v[134:137], v142 offset:1024
	ds_read_b128 v[138:141], v142 offset:2048
	ds_read_b128 v[142:145], v142 offset:3072
	ds_read_b128 v[146:149], v154
	ds_read_b128 v[172:175], v154 offset:1024
	ds_read_b128 v[176:179], v154 offset:2048
	ds_read_b128 v[210:213], v154 offset:3072
	s_add_u32 s12, s12, 0x2b0000
	s_addc_u32 s13, s13, 0
	s_mov_b32 m0, s50
	v_lshl_add_u64 v[188:189], s[12:13], 0, v[150:151]
	ds_read_b128 v[214:217], v202 offset:32768
	ds_read_b128 v[218:221], v202 offset:33792
	ds_read_b128 v[224:227], v202 offset:34816
	ds_read_b128 v[228:231], v202 offset:35840
	ds_read_b128 v[232:235], v202 offset:36864
	ds_read_b128 v[236:239], v202 offset:37888
	ds_read_b128 v[240:243], v202 offset:38912
	ds_read_b128 v[244:247], v202 offset:39936
	global_load_lds_dwordx4 v[188:189], off
	v_lshl_add_u64 v[188:189], s[12:13], 0, v[152:153]
	s_mov_b32 m0, s51
	s_nop 0
	global_load_lds_dwordx4 v[188:189], off
	s_waitcnt vmcnt(8)
	s_waitcnt lgkmcnt(0)
	s_setprio 1
	s_barrier
	v_mfma_f32_16x16x32_bf16 v[90:93], v[130:133], v[214:217], v[90:93]
	v_mfma_f32_16x16x32_bf16 v[74:77], v[138:141], v[214:217], v[74:77]
	v_mfma_f32_16x16x32_bf16 v[42:45], v[138:141], v[224:227], v[42:45]
	v_mfma_f32_16x16x32_bf16 v[46:49], v[130:133], v[224:227], v[46:49]
	v_mfma_f32_16x16x32_bf16 v[126:129], v[130:133], v[232:235], v[126:129]
	v_mfma_f32_16x16x32_bf16 v[122:125], v[138:141], v[232:235], v[122:125]
	v_mfma_f32_16x16x32_bf16 v[106:109], v[138:141], v[240:243], v[106:109]
	v_mfma_f32_16x16x32_bf16 v[110:113], v[130:133], v[240:243], v[110:113]
	v_mfma_f32_16x16x32_bf16 v[90:93], v[134:137], v[218:221], v[90:93]
	v_mfma_f32_16x16x32_bf16 v[74:77], v[142:145], v[218:221], v[74:77]
	v_mfma_f32_16x16x32_bf16 v[42:45], v[142:145], v[228:231], v[42:45]
	v_mfma_f32_16x16x32_bf16 v[46:49], v[134:137], v[228:231], v[46:49]
	v_mfma_f32_16x16x32_bf16 v[126:129], v[134:137], v[236:239], v[126:129]
	v_mfma_f32_16x16x32_bf16 v[122:125], v[142:145], v[236:239], v[122:125]
	v_mfma_f32_16x16x32_bf16 v[106:109], v[142:145], v[244:247], v[106:109]
	v_mfma_f32_16x16x32_bf16 v[110:113], v[134:137], v[244:247], v[110:113]
	s_setprio 0
	s_setprio 1
	v_mfma_f32_16x16x32_bf16 v[70:73], v[146:149], v[214:217], v[70:73]
	v_mfma_f32_16x16x32_bf16 v[66:69], v[176:179], v[214:217], v[66:69]
	v_mfma_f32_16x16x32_bf16 v[38:41], v[176:179], v[224:227], v[38:41]
	v_mfma_f32_16x16x32_bf16 v[34:37], v[146:149], v[224:227], v[34:37]
	v_mfma_f32_16x16x32_bf16 v[118:121], v[146:149], v[232:235], v[118:121]
	v_mfma_f32_16x16x32_bf16 v[114:117], v[176:179], v[232:235], v[114:117]
	v_mfma_f32_16x16x32_bf16 v[98:101], v[176:179], v[240:243], v[98:101]
	v_mfma_f32_16x16x32_bf16 v[102:105], v[146:149], v[240:243], v[102:105]
	v_mfma_f32_16x16x32_bf16 v[70:73], v[172:175], v[218:221], v[70:73]
	v_mfma_f32_16x16x32_bf16 v[66:69], v[210:213], v[218:221], v[66:69]
	v_mfma_f32_16x16x32_bf16 v[38:41], v[210:213], v[228:231], v[38:41]
	v_mfma_f32_16x16x32_bf16 v[34:37], v[172:175], v[228:231], v[34:37]
	v_mfma_f32_16x16x32_bf16 v[118:121], v[172:175], v[236:239], v[118:121]
	v_mfma_f32_16x16x32_bf16 v[114:117], v[210:213], v[236:239], v[114:117]
	v_mfma_f32_16x16x32_bf16 v[98:101], v[210:213], v[244:247], v[98:101]
	v_mfma_f32_16x16x32_bf16 v[102:105], v[172:175], v[244:247], v[102:105]
	s_barrier
	s_setprio 0
	s_add_i32 s12, s17, s46
	v_lshl_add_u64 v[180:181], v[180:181], 0, s[30:31]
	s_mov_b32 m0, s12
	ds_read_b128 v[214:217], v202 offset:49152
	ds_read_b128 v[218:221], v202 offset:50176
	ds_read_b128 v[224:227], v202 offset:51200
	ds_read_b128 v[228:231], v202 offset:52224
	ds_read_b128 v[232:235], v202 offset:53248
	ds_read_b128 v[236:239], v202 offset:54272
	ds_read_b128 v[240:243], v202 offset:55296
	ds_read_b128 v[244:247], v202 offset:56320
	global_load_lds_dwordx4 v[180:181], off
	s_add_i32 m0, s12, 0x2000
	s_add_u32 s10, s10, 0x2b0080
	v_lshl_add_u64 v[180:181], v[248:249], 0, s[30:31]
	s_addc_u32 s11, s11, 0
	s_add_i32 s12, s18, s46
	global_load_lds_dwordx4 v[180:181], off
	v_lshl_add_u64 v[180:181], s[10:11], 0, v[150:151]
	s_mov_b32 m0, s12
	s_nop 0
	global_load_lds_dwordx4 v[180:181], off
	v_lshl_add_u64 v[180:181], s[10:11], 0, v[152:153]
	s_add_i32 m0, s12, 0x2000
	s_nop 0
	global_load_lds_dwordx4 v[180:181], off
	v_lshl_add_u64 v[180:181], v[250:251], 0, s[30:31]
	s_mov_b32 m0, s52
	s_nop 0
	global_load_lds_dwordx4 v[180:181], off
	v_lshl_add_u64 v[180:181], v[252:253], 0, s[30:31]
	s_mov_b32 m0, s53
	s_nop 0
	global_load_lds_dwordx4 v[180:181], off
	s_waitcnt vmcnt(8)
	s_waitcnt lgkmcnt(0)
	s_setprio 1
	s_barrier
	v_mfma_f32_16x16x32_bf16 v[94:97], v[130:133], v[214:217], v[94:97]
	v_mfma_f32_16x16x32_bf16 v[86:89], v[138:141], v[214:217], v[86:89]
	v_mfma_f32_16x16x32_bf16 v[78:81], v[138:141], v[224:227], v[78:81]
	v_mfma_f32_16x16x32_bf16 v[82:85], v[130:133], v[224:227], v[82:85]
	v_mfma_f32_16x16x32_bf16 v[30:33], v[130:133], v[232:235], v[30:33]
	v_mfma_f32_16x16x32_bf16 v[26:29], v[138:141], v[232:235], v[26:29]
	v_mfma_f32_16x16x32_bf16 v[18:21], v[138:141], v[240:243], v[18:21]
	v_mfma_f32_16x16x32_bf16 v[22:25], v[130:133], v[240:243], v[22:25]
	v_mfma_f32_16x16x32_bf16 v[94:97], v[134:137], v[218:221], v[94:97]
	v_mfma_f32_16x16x32_bf16 v[86:89], v[142:145], v[218:221], v[86:89]
	v_mfma_f32_16x16x32_bf16 v[78:81], v[142:145], v[228:231], v[78:81]
	v_mfma_f32_16x16x32_bf16 v[82:85], v[134:137], v[228:231], v[82:85]
	v_mfma_f32_16x16x32_bf16 v[30:33], v[134:137], v[236:239], v[30:33]
	v_mfma_f32_16x16x32_bf16 v[26:29], v[142:145], v[236:239], v[26:29]
	v_mfma_f32_16x16x32_bf16 v[18:21], v[142:145], v[244:247], v[18:21]
	v_mfma_f32_16x16x32_bf16 v[22:25], v[134:137], v[244:247], v[22:25]
	s_setprio 0
	s_setprio 1
	v_mfma_f32_16x16x32_bf16 v[62:65], v[146:149], v[214:217], v[62:65]
	v_mfma_f32_16x16x32_bf16 v[58:61], v[176:179], v[214:217], v[58:61]
	v_mfma_f32_16x16x32_bf16 v[50:53], v[176:179], v[224:227], v[50:53]
	v_mfma_f32_16x16x32_bf16 v[54:57], v[146:149], v[224:227], v[54:57]
	v_mfma_f32_16x16x32_bf16 v[14:17], v[146:149], v[232:235], v[14:17]
	v_mfma_f32_16x16x32_bf16 v[6:9], v[176:179], v[232:235], v[6:9]
	v_mfma_f32_16x16x32_bf16 v[2:5], v[176:179], v[240:243], v[2:5]
	v_mfma_f32_16x16x32_bf16 v[10:13], v[146:149], v[240:243], v[10:13]
	v_mfma_f32_16x16x32_bf16 v[62:65], v[172:175], v[218:221], v[62:65]
	v_mfma_f32_16x16x32_bf16 v[58:61], v[210:213], v[218:221], v[58:61]
	v_mfma_f32_16x16x32_bf16 v[50:53], v[210:213], v[228:231], v[50:53]
	v_mfma_f32_16x16x32_bf16 v[54:57], v[172:175], v[228:231], v[54:57]
	v_mfma_f32_16x16x32_bf16 v[14:17], v[172:175], v[236:239], v[14:17]
	v_mfma_f32_16x16x32_bf16 v[6:9], v[210:213], v[236:239], v[6:9]
	v_mfma_f32_16x16x32_bf16 v[2:5], v[210:213], v[244:247], v[2:5]
	v_mfma_f32_16x16x32_bf16 v[10:13], v[172:175], v[244:247], v[10:13]
	s_barrier
	s_setprio 0
	s_add_i32 s16, s16, 2
	s_add_u32 s8, s8, 0x100
	s_addc_u32 s9, s9, 0
	s_add_u32 s14, s14, 0x100
	s_addc_u32 s15, s15, 0
	s_cmpk_gt_u32 s16, 0xa9
	s_cbranch_scc0 .LBB0_1040
	s_and_b64 vcc, exec, s[34:35]
	s_cbranch_vccz .LBB0_1043
	s_barrier

	.amdhsa_kernel _Z6mk_fwd4Args
		.amdhsa_group_segment_fixed_size 0
		.amdhsa_private_segment_fixed_size 0
		.amdhsa_kernarg_size 432
		.amdhsa_user_sgpr_count 2
		.amdhsa_user_sgpr_dispatch_ptr 0
		.amdhsa_user_sgpr_queue_ptr 0
		.amdhsa_user_sgpr_kernarg_segment_ptr 1
		.amdhsa_user_sgpr_dispatch_id 0
		.amdhsa_user_sgpr_kernarg_preload_length 0
		.amdhsa_user_sgpr_kernarg_preload_offset 0
		.amdhsa_user_sgpr_private_segment_size 0
		.amdhsa_uses_dynamic_stack 0
		.amdhsa_enable_private_segment 0
		.amdhsa_system_sgpr_workgroup_id_x 1
		.amdhsa_system_sgpr_workgroup_id_y 0
		.amdhsa_system_sgpr_workgroup_id_z 0
		.amdhsa_system_sgpr_workgroup_info 0
		.amdhsa_system_vgpr_workitem_id 0
		.amdhsa_next_free_vgpr 256
		.amdhsa_next_free_sgpr 99
		.amdhsa_accum_offset 256
		.amdhsa_reserve_vcc 1
		.amdhsa_float_round_mode_32 0
		.amdhsa_float_round_mode_16_64 0
		.amdhsa_float_denorm_mode_32 3
		.amdhsa_float_denorm_mode_16_64 3
		.amdhsa_dx10_clamp 1
		.amdhsa_ieee_mode 1
		.amdhsa_fp16_overflow 0
		.amdhsa_tg_split 0
		.amdhsa_exception_fp_ieee_invalid_op 0
		.amdhsa_exception_fp_denorm_src 0
		.amdhsa_exception_fp_ieee_div_zero 0
		.amdhsa_exception_fp_ieee_overflow 0
		.amdhsa_exception_fp_ieee_underflow 0
		.amdhsa_exception_fp_ieee_inexact 0
		.amdhsa_exception_int_div_zero 0
	.end_amdhsa_kernel

amdhsa.kernels:
  - .agpr_count:     0
    .args:
      - .offset:         0
        .size:           176
        .value_kind:     by_value
      - .offset:         176
        .size:           4
        .value_kind:     hidden_block_count_x
      - .offset:         180
        .size:           4
        .value_kind:     hidden_block_count_y
      - .offset:         184
        .size:           4
        .value_kind:     hidden_block_count_z
      - .offset:         188
        .size:           2
        .value_kind:     hidden_group_size_x
      - .offset:         190
        .size:           2
        .value_kind:     hidden_group_size_y
      - .offset:         192
        .size:           2
        .value_kind:     hidden_group_size_z
      - .offset:         194
        .size:           2
        .value_kind:     hidden_remainder_x
      - .offset:         196
        .size:           2
        .value_kind:     hidden_remainder_y
      - .offset:         198
        .size:           2
        .value_kind:     hidden_remainder_z
      - .offset:         216
        .size:           8
        .value_kind:     hidden_global_offset_x
      - .offset:         224
        .size:           8
        .value_kind:     hidden_global_offset_y
      - .offset:         232
        .size:           8
        .value_kind:     hidden_global_offset_z
      - .offset:         240
        .size:           2
        .value_kind:     hidden_grid_dims
      - .offset:         296
        .size:           4
        .value_kind:     hidden_dynamic_lds_size
    .group_segment_fixed_size: 0
    .kernarg_segment_align: 8
    .kernarg_segment_size: 432
    .language:       OpenCL C
    .language_version:
      - 2
      - 0
    .max_flat_workgroup_size: 512
    .name:           _Z6mk_fwd4Args
    .private_segment_fixed_size: 0
    .sgpr_count:     105
    .sgpr_spill_count: 27
    .symbol:         _Z6mk_fwd4Args.kd
    .uniform_work_group_size: 1
    .uses_dynamic_stack: false
    .vgpr_count:     256
    .vgpr_spill_count: 0
    .wavefront_size: 64
